# v32: EpiRes (phases 2/7/9) second-half residual loads issued early with first half into spare VGPRs; second-half vmcnt waits removed; VGPR alloc 256
# baseline (speedup 1.0000x reference)
.LBB0_265:
	s_mov_b32 s98, 0x40000
	s_mov_b32 s99, 0
	v_and_b32_e32 v121, 64, v230
	v_xor_b32_e32 v120, 16, v230
	v_add_u32_e32 v121, 64, v121
	v_cmp_lt_i32_e32 vcc, v120, v121
	s_lshl_b32 s42, s75, 8
	s_lshl_b32 s34, s15, 8
	v_cndmask_b32_e32 v120, v230, v120, vcc
	v_add_u32_e32 v156, s42, v225
	s_ashr_i32 s35, s34, 31
	v_lshlrev_b32_e32 v167, 2, v120
	v_xor_b32_e32 v120, 32, v230
	v_cmp_lt_i32_e32 vcc, v120, v121
	s_lshl_b64 s[34:35], s[34:35], 1
	v_ashrrev_i32_e32 v157, 31, v156
	v_cndmask_b32_e32 v120, v230, v120, vcc
	v_lshl_add_u64 v[158:159], v[204:205], 0, s[34:35]
	v_lshlrev_b64 v[172:173], 11, v[156:157]
	v_lshlrev_b32_e32 v166, 2, v120
	v_lshl_add_u64 v[120:121], v[158:159], 0, v[172:173]
	v_lshl_add_u64 v[190:191], v[120:121], 0, s[98:99]
	global_load_dwordx4 v[182:185], v[190:191], off
	global_load_dwordx4 v[186:189], v[190:191], off offset:256
	global_load_dwordx4 v[168:171], v[120:121], off
	global_load_dwordx4 v[152:155], v[120:121], off offset:256
	v_or_b32_e32 v120, 16, v156
	v_ashrrev_i32_e32 v121, 31, v120
	v_lshlrev_b64 v[164:165], 11, v[120:121]
	v_lshl_add_u64 v[120:121], v[158:159], 0, v[164:165]
	v_lshl_add_u64 v[190:191], v[120:121], 0, s[98:99]
	global_load_dwordx4 v[216:219], v[190:191], off
	global_load_dwordx4 v[220:223], v[190:191], off offset:256
	global_load_dwordx4 v[148:151], v[120:121], off
	global_load_dwordx4 v[144:147], v[120:121], off offset:256
	v_or_b32_e32 v120, 32, v156
	v_ashrrev_i32_e32 v121, 31, v120
	v_lshlrev_b64 v[162:163], 11, v[120:121]
	v_lshl_add_u64 v[120:121], v[158:159], 0, v[162:163]
	v_lshl_add_u64 v[190:191], v[120:121], 0, s[98:99]
	global_load_dwordx4 v[236:239], v[190:191], off
	global_load_dwordx4 v[240:243], v[190:191], off offset:256
	global_load_dwordx4 v[140:143], v[120:121], off
	global_load_dwordx4 v[136:139], v[120:121], off offset:256
	v_or_b32_e32 v120, 48, v156
	v_ashrrev_i32_e32 v121, 31, v120
	v_lshlrev_b64 v[160:161], 11, v[120:121]
	v_lshl_add_u64 v[120:121], v[158:159], 0, v[160:161]
	v_lshl_add_u64 v[190:191], v[120:121], 0, s[98:99]
	global_load_dwordx4 v[246:249], v[190:191], off
	global_load_dwordx4 v[250:253], v[190:191], off offset:256
	global_load_dwordx4 v[132:135], v[120:121], off
	s_nop 0
	global_load_dwordx4 v[120:123], v[120:121], off offset:256
	s_mov_b32 s15, s1
	s_ashr_i32 s43, s42, 31
	s_waitcnt vmcnt(0)
	v_lshlrev_b32_e32 v174, 16, v168
	v_and_b32_e32 v175, 0xffff0000, v168
	v_lshlrev_b32_e32 v168, 16, v169
	v_and_b32_e32 v169, 0xffff0000, v169
	v_pk_fma_f32 v[130:131], v[130:131], 0.5, v[168:169] op_sel_hi:[1,0,1]
	v_pk_fma_f32 v[168:169], v[128:129], 0.5, v[174:175] op_sel_hi:[1,0,1]
	v_cvt_pk_bf16_f32 v129, v130, v131
	v_mul_f32_e32 v157, v169, v169
	v_mul_f32_e32 v131, v131, v131
	v_fmac_f32_e32 v157, v168, v168
	v_fmac_f32_e32 v131, v130, v130
	v_add_f32_e32 v157, v157, v131
	v_lshlrev_b32_e32 v130, 16, v170
	v_and_b32_e32 v131, 0xffff0000, v170
	v_cvt_pk_bf16_f32 v128, v168, v169
	v_lshlrev_b32_e32 v168, 16, v171
	v_and_b32_e32 v169, 0xffff0000, v171
	v_pk_fma_f32 v[124:125], v[124:125], 0.5, v[130:131] op_sel_hi:[1,0,1]
	v_pk_fma_f32 v[126:127], v[126:127], 0.5, v[168:169] op_sel_hi:[1,0,1]
	v_cvt_pk_bf16_f32 v130, v124, v125
	v_mul_f32_e32 v125, v125, v125
	v_fmac_f32_e32 v125, v124, v124
	v_mul_f32_e32 v124, v127, v127
	v_fmac_f32_e32 v124, v126, v126
	v_add_f32_e32 v124, v125, v124
	v_add_f32_e32 v157, v157, v124
	v_lshl_add_u64 v[124:125], s[78:79], 0, v[172:173]
	v_lshl_add_u64 v[124:125], v[124:125], 0, s[34:35]
	v_lshl_add_u64 v[124:125], v[124:125], 0, s[14:15]
	v_cvt_pk_bf16_f32 v131, v126, v127
	v_lshl_add_u64 v[124:125], v[124:125], 0, v[200:201]
	global_store_dwordx4 v[124:125], v[128:131], off
	v_lshlrev_b32_e32 v126, 16, v152
	v_and_b32_e32 v127, 0xffff0000, v152
	v_lshlrev_b32_e32 v128, 16, v153
	v_and_b32_e32 v129, 0xffff0000, v153
	v_pk_fma_f32 v[118:119], v[118:119], 0.5, v[128:129] op_sel_hi:[1,0,1]
	v_pk_fma_f32 v[126:127], v[116:117], 0.5, v[126:127] op_sel_hi:[1,0,1]
	v_cvt_pk_bf16_f32 v117, v118, v119
	v_cvt_pk_bf16_f32 v116, v126, v127
	v_mul_f32_e32 v127, v127, v127
	v_mul_f32_e32 v119, v119, v119
	v_fmac_f32_e32 v127, v126, v126
	v_fmac_f32_e32 v119, v118, v118
	v_add_f32_e32 v118, v127, v119
	v_add_f32_e32 v128, v157, v118
	v_lshlrev_b32_e32 v118, 16, v154
	v_and_b32_e32 v119, 0xffff0000, v154
	v_lshlrev_b32_e32 v126, 16, v155
	v_and_b32_e32 v127, 0xffff0000, v155
	v_pk_fma_f32 v[112:113], v[112:113], 0.5, v[118:119] op_sel_hi:[1,0,1]
	v_pk_fma_f32 v[114:115], v[114:115], 0.5, v[126:127] op_sel_hi:[1,0,1]
	v_cvt_pk_bf16_f32 v118, v112, v113
	v_mul_f32_e32 v113, v113, v113
	v_cvt_pk_bf16_f32 v119, v114, v115
	v_fmac_f32_e32 v113, v112, v112
	v_mul_f32_e32 v112, v115, v115
	v_fmac_f32_e32 v112, v114, v114
	global_store_dwordx4 v[124:125], v[116:119], off offset:256
	v_lshlrev_b32_e32 v114, 16, v148
	v_and_b32_e32 v115, 0xffff0000, v148
	v_lshlrev_b32_e32 v116, 16, v149
	v_and_b32_e32 v117, 0xffff0000, v149
	v_pk_fma_f32 v[110:111], v[110:111], 0.5, v[116:117] op_sel_hi:[1,0,1]
	v_pk_fma_f32 v[114:115], v[108:109], 0.5, v[114:115] op_sel_hi:[1,0,1]
	v_cvt_pk_bf16_f32 v109, v110, v111
	v_cvt_pk_bf16_f32 v108, v114, v115
	v_mul_f32_e32 v115, v115, v115
	v_mul_f32_e32 v111, v111, v111
	v_fmac_f32_e32 v115, v114, v114
	v_fmac_f32_e32 v111, v110, v110
	v_add_f32_e32 v116, v115, v111
	v_lshlrev_b32_e32 v110, 16, v150
	v_and_b32_e32 v111, 0xffff0000, v150
	v_lshlrev_b32_e32 v114, 16, v151
	v_and_b32_e32 v115, 0xffff0000, v151
	v_pk_fma_f32 v[104:105], v[104:105], 0.5, v[110:111] op_sel_hi:[1,0,1]
	v_pk_fma_f32 v[106:107], v[106:107], 0.5, v[114:115] op_sel_hi:[1,0,1]
	v_cvt_pk_bf16_f32 v110, v104, v105
	v_mul_f32_e32 v105, v105, v105
	v_fmac_f32_e32 v105, v104, v104
	v_mul_f32_e32 v104, v107, v107
	v_fmac_f32_e32 v104, v106, v106
	v_add_f32_e32 v104, v105, v104
	v_add_f32_e32 v114, v116, v104
	v_lshl_add_u64 v[104:105], s[78:79], 0, v[164:165]
	v_lshl_add_u64 v[104:105], v[104:105], 0, s[34:35]
	v_lshl_add_u64 v[104:105], v[104:105], 0, s[14:15]
	v_cvt_pk_bf16_f32 v111, v106, v107
	v_lshl_add_u64 v[104:105], v[104:105], 0, v[200:201]
	global_store_dwordx4 v[104:105], v[108:111], off
	v_lshlrev_b32_e32 v106, 16, v144
	v_and_b32_e32 v107, 0xffff0000, v144
	v_lshlrev_b32_e32 v108, 16, v145
	v_and_b32_e32 v109, 0xffff0000, v145
	v_pk_fma_f32 v[102:103], v[102:103], 0.5, v[108:109] op_sel_hi:[1,0,1]
	v_pk_fma_f32 v[106:107], v[100:101], 0.5, v[106:107] op_sel_hi:[1,0,1]
	v_cvt_pk_bf16_f32 v101, v102, v103
	v_cvt_pk_bf16_f32 v100, v106, v107
	v_mul_f32_e32 v107, v107, v107
	v_mul_f32_e32 v103, v103, v103
	v_fmac_f32_e32 v107, v106, v106
	v_fmac_f32_e32 v103, v102, v102
	v_add_f32_e32 v102, v107, v103
	v_add_f32_e32 v108, v114, v102
	v_lshlrev_b32_e32 v102, 16, v146
	v_and_b32_e32 v103, 0xffff0000, v146
	v_lshlrev_b32_e32 v106, 16, v147
	v_and_b32_e32 v107, 0xffff0000, v147
	v_pk_fma_f32 v[96:97], v[96:97], 0.5, v[102:103] op_sel_hi:[1,0,1]
	v_pk_fma_f32 v[98:99], v[98:99], 0.5, v[106:107] op_sel_hi:[1,0,1]
	v_cvt_pk_bf16_f32 v102, v96, v97
	v_mul_f32_e32 v97, v97, v97
	v_cvt_pk_bf16_f32 v103, v98, v99
	v_fmac_f32_e32 v97, v96, v96
	v_mul_f32_e32 v96, v99, v99
	v_fmac_f32_e32 v96, v98, v98
	global_store_dwordx4 v[104:105], v[100:103], off offset:256
	v_lshlrev_b32_e32 v98, 16, v140
	v_and_b32_e32 v99, 0xffff0000, v140
	v_lshlrev_b32_e32 v100, 16, v141
	v_and_b32_e32 v101, 0xffff0000, v141
	v_pk_fma_f32 v[94:95], v[94:95], 0.5, v[100:101] op_sel_hi:[1,0,1]
	v_pk_fma_f32 v[98:99], v[92:93], 0.5, v[98:99] op_sel_hi:[1,0,1]
	v_cvt_pk_bf16_f32 v93, v94, v95
	v_cvt_pk_bf16_f32 v92, v98, v99
	v_mul_f32_e32 v99, v99, v99
	v_mul_f32_e32 v95, v95, v95
	v_fmac_f32_e32 v99, v98, v98
	v_fmac_f32_e32 v95, v94, v94
	v_add_f32_e32 v100, v99, v95
	v_lshlrev_b32_e32 v94, 16, v142
	v_and_b32_e32 v95, 0xffff0000, v142
	v_lshlrev_b32_e32 v98, 16, v143
	v_and_b32_e32 v99, 0xffff0000, v143
	v_pk_fma_f32 v[88:89], v[88:89], 0.5, v[94:95] op_sel_hi:[1,0,1]
	v_pk_fma_f32 v[90:91], v[90:91], 0.5, v[98:99] op_sel_hi:[1,0,1]
	v_cvt_pk_bf16_f32 v94, v88, v89
	v_mul_f32_e32 v89, v89, v89
	v_fmac_f32_e32 v89, v88, v88
	v_mul_f32_e32 v88, v91, v91
	v_fmac_f32_e32 v88, v90, v90
	v_add_f32_e32 v88, v89, v88
	v_add_f32_e32 v98, v100, v88
	v_lshl_add_u64 v[88:89], s[78:79], 0, v[162:163]
	v_lshl_add_u64 v[88:89], v[88:89], 0, s[34:35]
	v_lshl_add_u64 v[88:89], v[88:89], 0, s[14:15]
	v_cvt_pk_bf16_f32 v95, v90, v91
	v_lshl_add_u64 v[88:89], v[88:89], 0, v[200:201]
	global_store_dwordx4 v[88:89], v[92:95], off
	v_lshlrev_b32_e32 v90, 16, v136
	v_and_b32_e32 v91, 0xffff0000, v136
	v_lshlrev_b32_e32 v92, 16, v137
	v_and_b32_e32 v93, 0xffff0000, v137
	v_pk_fma_f32 v[86:87], v[86:87], 0.5, v[92:93] op_sel_hi:[1,0,1]
	v_pk_fma_f32 v[90:91], v[84:85], 0.5, v[90:91] op_sel_hi:[1,0,1]
	v_cvt_pk_bf16_f32 v85, v86, v87
	v_cvt_pk_bf16_f32 v84, v90, v91
	v_mul_f32_e32 v91, v91, v91
	v_mul_f32_e32 v87, v87, v87
	v_fmac_f32_e32 v91, v90, v90
	v_fmac_f32_e32 v87, v86, v86
	v_add_f32_e32 v86, v91, v87
	v_add_f32_e32 v92, v98, v86
	v_lshlrev_b32_e32 v86, 16, v138
	v_and_b32_e32 v87, 0xffff0000, v138
	v_lshlrev_b32_e32 v90, 16, v139
	v_and_b32_e32 v91, 0xffff0000, v139
	v_pk_fma_f32 v[80:81], v[80:81], 0.5, v[86:87] op_sel_hi:[1,0,1]
	v_pk_fma_f32 v[82:83], v[82:83], 0.5, v[90:91] op_sel_hi:[1,0,1]
	v_cvt_pk_bf16_f32 v86, v80, v81
	v_mul_f32_e32 v81, v81, v81
	v_cvt_pk_bf16_f32 v87, v82, v83
	v_fmac_f32_e32 v81, v80, v80
	v_mul_f32_e32 v80, v83, v83
	v_fmac_f32_e32 v80, v82, v82
	global_store_dwordx4 v[88:89], v[84:87], off offset:256
	v_lshlrev_b32_e32 v82, 16, v132
	v_and_b32_e32 v83, 0xffff0000, v132
	v_lshlrev_b32_e32 v84, 16, v133
	v_and_b32_e32 v85, 0xffff0000, v133
	v_pk_fma_f32 v[78:79], v[78:79], 0.5, v[84:85] op_sel_hi:[1,0,1]
	v_pk_fma_f32 v[82:83], v[76:77], 0.5, v[82:83] op_sel_hi:[1,0,1]
	v_cvt_pk_bf16_f32 v77, v78, v79
	v_cvt_pk_bf16_f32 v76, v82, v83
	v_mul_f32_e32 v83, v83, v83
	v_mul_f32_e32 v79, v79, v79
	v_fmac_f32_e32 v83, v82, v82
	v_fmac_f32_e32 v79, v78, v78
	v_add_f32_e32 v84, v83, v79
	v_lshlrev_b32_e32 v78, 16, v134
	v_and_b32_e32 v79, 0xffff0000, v134
	v_lshlrev_b32_e32 v82, 16, v135
	v_and_b32_e32 v83, 0xffff0000, v135
	v_pk_fma_f32 v[72:73], v[72:73], 0.5, v[78:79] op_sel_hi:[1,0,1]
	v_pk_fma_f32 v[74:75], v[74:75], 0.5, v[82:83] op_sel_hi:[1,0,1]
	v_cvt_pk_bf16_f32 v78, v72, v73
	v_mul_f32_e32 v73, v73, v73
	v_fmac_f32_e32 v73, v72, v72
	v_mul_f32_e32 v72, v75, v75
	v_fmac_f32_e32 v72, v74, v74
	v_add_f32_e32 v72, v73, v72
	v_add_f32_e32 v82, v84, v72
	v_lshl_add_u64 v[72:73], s[78:79], 0, v[160:161]
	v_lshl_add_u64 v[72:73], v[72:73], 0, s[34:35]
	v_lshl_add_u64 v[72:73], v[72:73], 0, s[14:15]
	v_cvt_pk_bf16_f32 v79, v74, v75
	v_lshl_add_u64 v[72:73], v[72:73], 0, v[200:201]
	global_store_dwordx4 v[72:73], v[76:79], off
	v_lshlrev_b32_e32 v74, 16, v120
	v_and_b32_e32 v75, 0xffff0000, v120
	v_lshlrev_b32_e32 v76, 16, v121
	v_and_b32_e32 v77, 0xffff0000, v121
	v_pk_fma_f32 v[70:71], v[70:71], 0.5, v[76:77] op_sel_hi:[1,0,1]
	v_pk_fma_f32 v[74:75], v[68:69], 0.5, v[74:75] op_sel_hi:[1,0,1]
	v_cvt_pk_bf16_f32 v69, v70, v71
	v_cvt_pk_bf16_f32 v68, v74, v75
	v_mul_f32_e32 v75, v75, v75
	v_mul_f32_e32 v71, v71, v71
	v_fmac_f32_e32 v75, v74, v74
	v_fmac_f32_e32 v71, v70, v70
	v_add_f32_e32 v70, v75, v71
	v_add_f32_e32 v76, v82, v70
	v_lshlrev_b32_e32 v70, 16, v122
	v_and_b32_e32 v71, 0xffff0000, v122
	v_lshlrev_b32_e32 v74, 16, v123
	v_and_b32_e32 v75, 0xffff0000, v123
	v_pk_fma_f32 v[64:65], v[64:65], 0.5, v[70:71] op_sel_hi:[1,0,1]
	v_pk_fma_f32 v[66:67], v[66:67], 0.5, v[74:75] op_sel_hi:[1,0,1]
	v_cvt_pk_bf16_f32 v70, v64, v65
	v_mul_f32_e32 v65, v65, v65
	v_fmac_f32_e32 v65, v64, v64
	v_mul_f32_e32 v64, v67, v67
	v_fmac_f32_e32 v64, v66, v66
	v_add_f32_e32 v112, v113, v112
	v_add_f32_e32 v96, v97, v96
	v_add_f32_e32 v80, v81, v80
	v_add_f32_e32 v64, v65, v64
	v_add_f32_e32 v112, v112, v128
	v_add_f32_e32 v96, v96, v108
	v_add_f32_e32 v80, v80, v92
	v_add_f32_e32 v64, v64, v76
	ds_bpermute_b32 v113, v167, v112
	ds_bpermute_b32 v97, v167, v96
	ds_bpermute_b32 v81, v167, v80
	ds_bpermute_b32 v65, v167, v64
	v_cvt_pk_bf16_f32 v71, v66, v67
	s_waitcnt lgkmcnt(3)
	v_add_f32_e32 v112, v112, v113
	s_waitcnt lgkmcnt(2)
	v_add_f32_e32 v96, v96, v97
	s_waitcnt lgkmcnt(1)
	v_add_f32_e32 v80, v80, v81
	s_waitcnt lgkmcnt(0)
	v_add_f32_e32 v64, v64, v65
	ds_bpermute_b32 v113, v166, v112
	ds_bpermute_b32 v97, v166, v96
	ds_bpermute_b32 v81, v166, v80
	ds_bpermute_b32 v65, v166, v64
	v_lshl_add_u64 v[92:93], s[42:43], 2, v[206:207]
	global_store_dwordx4 v[72:73], v[68:71], off offset:256
	s_and_saveexec_b64 s[42:43], s[2:3]
	v_readlane_b32 s92, v245, 60
	v_readlane_b32 s93, v245, 61
	v_readlane_b32 s94, v245, 62
	v_readlane_b32 s95, v245, 63
	v_readlane_b32 s97, v244, 0
	s_cbranch_execz .LBB0_267
	s_waitcnt lgkmcnt(3)
	v_add_f32_e32 v67, v112, v113
	s_waitcnt lgkmcnt(0)
	v_add_f32_e32 v64, v64, v65
	v_add_f32_e32 v65, v80, v81
	v_add_f32_e32 v66, v96, v97
	global_atomic_add_f32 v[92:93], v67, off
	global_atomic_add_f32 v[92:93], v66, off offset:64
	global_atomic_add_f32 v[92:93], v65, off offset:128
	global_atomic_add_f32 v[92:93], v64, off offset:192
.LBB0_267:
	s_or_b64 exec, exec, s[42:43]
	v_add_u32_e32 v64, 0x80, v156
	s_waitcnt lgkmcnt(0)
	v_ashrrev_i32_e32 v65, 31, v64
	v_lshlrev_b64 v[104:105], 11, v[64:65]
	v_lshl_add_u64 v[64:65], v[158:159], 0, v[104:105]
	v_mov_b32_e32 v100, v182
	v_mov_b32_e32 v101, v183
	v_mov_b32_e32 v102, v184
	v_mov_b32_e32 v103, v185
	v_mov_b32_e32 v88, v186
	v_mov_b32_e32 v89, v187
	v_mov_b32_e32 v90, v188
	v_mov_b32_e32 v91, v189
	v_add_u32_e32 v64, 0x90, v156
	v_ashrrev_i32_e32 v65, 31, v64
	v_lshlrev_b64 v[98:99], 11, v[64:65]
	v_lshl_add_u64 v[64:65], v[158:159], 0, v[98:99]
	v_mov_b32_e32 v84, v216
	v_mov_b32_e32 v85, v217
	v_mov_b32_e32 v86, v218
	v_mov_b32_e32 v87, v219
	v_mov_b32_e32 v80, v220
	v_mov_b32_e32 v81, v221
	v_mov_b32_e32 v82, v222
	v_mov_b32_e32 v83, v223
	v_add_u32_e32 v64, 0xa0, v156
	v_ashrrev_i32_e32 v65, 31, v64
	v_lshlrev_b64 v[96:97], 11, v[64:65]
	v_lshl_add_u64 v[64:65], v[158:159], 0, v[96:97]
	v_mov_b32_e32 v76, v236
	v_mov_b32_e32 v77, v237
	v_mov_b32_e32 v78, v238
	v_mov_b32_e32 v79, v239
	v_mov_b32_e32 v72, v240
	v_mov_b32_e32 v73, v241
	v_mov_b32_e32 v74, v242
	v_mov_b32_e32 v75, v243
	v_add_u32_e32 v64, 0xb0, v156
	v_ashrrev_i32_e32 v65, 31, v64
	v_lshlrev_b64 v[94:95], 11, v[64:65]
	v_lshl_add_u64 v[64:65], v[158:159], 0, v[94:95]
	v_mov_b32_e32 v68, v246
	v_mov_b32_e32 v69, v247
	v_mov_b32_e32 v70, v248
	v_mov_b32_e32 v71, v249
	s_nop 0
	v_mov_b32_e32 v64, v250
	v_mov_b32_e32 v65, v251
	v_mov_b32_e32 v66, v252
	v_mov_b32_e32 v67, v253
	v_lshlrev_b32_e32 v106, 16, v100
	v_and_b32_e32 v107, 0xffff0000, v100
	v_lshlrev_b32_e32 v100, 16, v101
	v_and_b32_e32 v101, 0xffff0000, v101
	v_pk_fma_f32 v[62:63], v[62:63], 0.5, v[100:101] op_sel_hi:[1,0,1]
	v_pk_fma_f32 v[100:101], v[60:61], 0.5, v[106:107] op_sel_hi:[1,0,1]
	v_cvt_pk_bf16_f32 v61, v62, v63
	v_cvt_pk_bf16_f32 v60, v100, v101
	v_mul_f32_e32 v101, v101, v101
	v_mul_f32_e32 v63, v63, v63
	v_fmac_f32_e32 v101, v100, v100
	v_fmac_f32_e32 v63, v62, v62
	v_add_f32_e32 v106, v101, v63
	v_lshlrev_b32_e32 v62, 16, v102
	v_and_b32_e32 v63, 0xffff0000, v102
	v_lshlrev_b32_e32 v100, 16, v103
	v_and_b32_e32 v101, 0xffff0000, v103
	v_pk_fma_f32 v[56:57], v[56:57], 0.5, v[62:63] op_sel_hi:[1,0,1]
	v_pk_fma_f32 v[58:59], v[58:59], 0.5, v[100:101] op_sel_hi:[1,0,1]
	v_cvt_pk_bf16_f32 v62, v56, v57
	v_mul_f32_e32 v57, v57, v57
	v_fmac_f32_e32 v57, v56, v56
	v_mul_f32_e32 v56, v59, v59
	v_fmac_f32_e32 v56, v58, v58
	v_add_f32_e32 v56, v57, v56
	v_add_f32_e32 v100, v106, v56
	v_lshl_add_u64 v[56:57], s[78:79], 0, v[104:105]
	v_lshl_add_u64 v[56:57], v[56:57], 0, s[34:35]
	v_lshl_add_u64 v[56:57], v[56:57], 0, s[14:15]
	v_cvt_pk_bf16_f32 v63, v58, v59
	v_lshl_add_u64 v[56:57], v[56:57], 0, v[200:201]
	global_store_dwordx4 v[56:57], v[60:63], off
	v_lshlrev_b32_e32 v58, 16, v88
	v_and_b32_e32 v59, 0xffff0000, v88
	v_lshlrev_b32_e32 v60, 16, v89
	v_and_b32_e32 v61, 0xffff0000, v89
	v_pk_fma_f32 v[54:55], v[54:55], 0.5, v[60:61] op_sel_hi:[1,0,1]
	v_pk_fma_f32 v[58:59], v[52:53], 0.5, v[58:59] op_sel_hi:[1,0,1]
	v_cvt_pk_bf16_f32 v53, v54, v55
	v_cvt_pk_bf16_f32 v52, v58, v59
	v_mul_f32_e32 v59, v59, v59
	v_mul_f32_e32 v55, v55, v55
	v_fmac_f32_e32 v59, v58, v58
	v_fmac_f32_e32 v55, v54, v54
	v_add_f32_e32 v54, v59, v55
	v_add_f32_e32 v60, v100, v54
	v_lshlrev_b32_e32 v54, 16, v90
	v_and_b32_e32 v55, 0xffff0000, v90
	v_lshlrev_b32_e32 v58, 16, v91
	v_and_b32_e32 v59, 0xffff0000, v91
	v_pk_fma_f32 v[48:49], v[48:49], 0.5, v[54:55] op_sel_hi:[1,0,1]
	v_pk_fma_f32 v[50:51], v[50:51], 0.5, v[58:59] op_sel_hi:[1,0,1]
	v_cvt_pk_bf16_f32 v54, v48, v49
	v_mul_f32_e32 v49, v49, v49
	v_cvt_pk_bf16_f32 v55, v50, v51
	v_fmac_f32_e32 v49, v48, v48
	v_mul_f32_e32 v48, v51, v51
	v_fmac_f32_e32 v48, v50, v50
	global_store_dwordx4 v[56:57], v[52:55], off offset:256
	v_lshlrev_b32_e32 v50, 16, v84
	v_and_b32_e32 v51, 0xffff0000, v84
	v_lshlrev_b32_e32 v52, 16, v85
	v_and_b32_e32 v53, 0xffff0000, v85
	v_pk_fma_f32 v[46:47], v[46:47], 0.5, v[52:53] op_sel_hi:[1,0,1]
	v_pk_fma_f32 v[50:51], v[44:45], 0.5, v[50:51] op_sel_hi:[1,0,1]
	v_cvt_pk_bf16_f32 v45, v46, v47
	v_cvt_pk_bf16_f32 v44, v50, v51
	v_mul_f32_e32 v51, v51, v51
	v_mul_f32_e32 v47, v47, v47
	v_fmac_f32_e32 v51, v50, v50
	v_fmac_f32_e32 v47, v46, v46
	v_add_f32_e32 v52, v51, v47
	v_lshlrev_b32_e32 v46, 16, v86
	v_and_b32_e32 v47, 0xffff0000, v86
	v_lshlrev_b32_e32 v50, 16, v87
	v_and_b32_e32 v51, 0xffff0000, v87
	v_pk_fma_f32 v[40:41], v[40:41], 0.5, v[46:47] op_sel_hi:[1,0,1]
	v_pk_fma_f32 v[42:43], v[42:43], 0.5, v[50:51] op_sel_hi:[1,0,1]
	v_cvt_pk_bf16_f32 v46, v40, v41
	v_mul_f32_e32 v41, v41, v41
	v_fmac_f32_e32 v41, v40, v40
	v_mul_f32_e32 v40, v43, v43
	v_fmac_f32_e32 v40, v42, v42
	v_add_f32_e32 v40, v41, v40
	v_add_f32_e32 v50, v52, v40
	v_lshl_add_u64 v[40:41], s[78:79], 0, v[98:99]
	v_lshl_add_u64 v[40:41], v[40:41], 0, s[34:35]
	v_lshl_add_u64 v[40:41], v[40:41], 0, s[14:15]
	v_cvt_pk_bf16_f32 v47, v42, v43
	v_lshl_add_u64 v[40:41], v[40:41], 0, v[200:201]
	global_store_dwordx4 v[40:41], v[44:47], off
	v_lshlrev_b32_e32 v42, 16, v80
	v_and_b32_e32 v43, 0xffff0000, v80
	v_lshlrev_b32_e32 v44, 16, v81
	v_and_b32_e32 v45, 0xffff0000, v81
	v_pk_fma_f32 v[38:39], v[38:39], 0.5, v[44:45] op_sel_hi:[1,0,1]
	v_pk_fma_f32 v[42:43], v[36:37], 0.5, v[42:43] op_sel_hi:[1,0,1]
	v_cvt_pk_bf16_f32 v37, v38, v39
	v_cvt_pk_bf16_f32 v36, v42, v43
	v_mul_f32_e32 v43, v43, v43
	v_mul_f32_e32 v39, v39, v39
	v_fmac_f32_e32 v43, v42, v42
	v_fmac_f32_e32 v39, v38, v38
	v_add_f32_e32 v38, v43, v39
	v_add_f32_e32 v44, v50, v38
	v_lshlrev_b32_e32 v38, 16, v82
	v_and_b32_e32 v39, 0xffff0000, v82
	v_lshlrev_b32_e32 v42, 16, v83
	v_and_b32_e32 v43, 0xffff0000, v83
	v_pk_fma_f32 v[32:33], v[32:33], 0.5, v[38:39] op_sel_hi:[1,0,1]
	v_pk_fma_f32 v[34:35], v[34:35], 0.5, v[42:43] op_sel_hi:[1,0,1]
	v_cvt_pk_bf16_f32 v38, v32, v33
	v_mul_f32_e32 v33, v33, v33
	v_cvt_pk_bf16_f32 v39, v34, v35
	v_fmac_f32_e32 v33, v32, v32
	v_mul_f32_e32 v32, v35, v35
	v_fmac_f32_e32 v32, v34, v34
	global_store_dwordx4 v[40:41], v[36:39], off offset:256
	v_lshlrev_b32_e32 v34, 16, v76
	v_and_b32_e32 v35, 0xffff0000, v76
	v_lshlrev_b32_e32 v36, 16, v77
	v_and_b32_e32 v37, 0xffff0000, v77
	v_pk_fma_f32 v[30:31], v[30:31], 0.5, v[36:37] op_sel_hi:[1,0,1]
	v_pk_fma_f32 v[34:35], v[28:29], 0.5, v[34:35] op_sel_hi:[1,0,1]
	v_cvt_pk_bf16_f32 v29, v30, v31
	v_cvt_pk_bf16_f32 v28, v34, v35
	v_mul_f32_e32 v35, v35, v35
	v_mul_f32_e32 v31, v31, v31
	v_fmac_f32_e32 v35, v34, v34
	v_fmac_f32_e32 v31, v30, v30
	v_add_f32_e32 v36, v35, v31
	v_lshlrev_b32_e32 v30, 16, v78
	v_and_b32_e32 v31, 0xffff0000, v78
	v_lshlrev_b32_e32 v34, 16, v79
	v_and_b32_e32 v35, 0xffff0000, v79
	v_pk_fma_f32 v[24:25], v[24:25], 0.5, v[30:31] op_sel_hi:[1,0,1]
	v_pk_fma_f32 v[26:27], v[26:27], 0.5, v[34:35] op_sel_hi:[1,0,1]
	v_cvt_pk_bf16_f32 v30, v24, v25
	v_mul_f32_e32 v25, v25, v25
	v_fmac_f32_e32 v25, v24, v24
	v_mul_f32_e32 v24, v27, v27
	v_fmac_f32_e32 v24, v26, v26
	v_add_f32_e32 v24, v25, v24
	v_add_f32_e32 v34, v36, v24
	v_lshl_add_u64 v[24:25], s[78:79], 0, v[96:97]
	v_lshl_add_u64 v[24:25], v[24:25], 0, s[34:35]
	v_lshl_add_u64 v[24:25], v[24:25], 0, s[14:15]
	v_cvt_pk_bf16_f32 v31, v26, v27
	v_lshl_add_u64 v[24:25], v[24:25], 0, v[200:201]
	global_store_dwordx4 v[24:25], v[28:31], off
	v_lshlrev_b32_e32 v26, 16, v72
	v_and_b32_e32 v27, 0xffff0000, v72
	v_lshlrev_b32_e32 v28, 16, v73
	v_and_b32_e32 v29, 0xffff0000, v73
	v_pk_fma_f32 v[22:23], v[22:23], 0.5, v[28:29] op_sel_hi:[1,0,1]
	v_pk_fma_f32 v[26:27], v[20:21], 0.5, v[26:27] op_sel_hi:[1,0,1]
	v_cvt_pk_bf16_f32 v21, v22, v23
	v_cvt_pk_bf16_f32 v20, v26, v27
	v_mul_f32_e32 v27, v27, v27
	v_mul_f32_e32 v23, v23, v23
	v_fmac_f32_e32 v27, v26, v26
	v_fmac_f32_e32 v23, v22, v22
	v_add_f32_e32 v22, v27, v23
	v_add_f32_e32 v28, v34, v22
	v_lshlrev_b32_e32 v22, 16, v74
	v_and_b32_e32 v23, 0xffff0000, v74
	v_lshlrev_b32_e32 v26, 16, v75
	v_and_b32_e32 v27, 0xffff0000, v75
	v_pk_fma_f32 v[16:17], v[16:17], 0.5, v[22:23] op_sel_hi:[1,0,1]
	v_pk_fma_f32 v[18:19], v[18:19], 0.5, v[26:27] op_sel_hi:[1,0,1]
	v_cvt_pk_bf16_f32 v22, v16, v17
	v_mul_f32_e32 v17, v17, v17
	v_cvt_pk_bf16_f32 v23, v18, v19
	v_fmac_f32_e32 v17, v16, v16
	v_mul_f32_e32 v16, v19, v19
	v_fmac_f32_e32 v16, v18, v18
	global_store_dwordx4 v[24:25], v[20:23], off offset:256
	v_lshlrev_b32_e32 v18, 16, v68
	v_and_b32_e32 v19, 0xffff0000, v68
	v_lshlrev_b32_e32 v20, 16, v69
	v_and_b32_e32 v21, 0xffff0000, v69
	v_pk_fma_f32 v[14:15], v[14:15], 0.5, v[20:21] op_sel_hi:[1,0,1]
	v_pk_fma_f32 v[18:19], v[12:13], 0.5, v[18:19] op_sel_hi:[1,0,1]
	v_cvt_pk_bf16_f32 v13, v14, v15
	v_cvt_pk_bf16_f32 v12, v18, v19
	v_mul_f32_e32 v19, v19, v19
	v_mul_f32_e32 v15, v15, v15
	v_fmac_f32_e32 v19, v18, v18
	v_fmac_f32_e32 v15, v14, v14
	v_add_f32_e32 v20, v19, v15
	v_lshlrev_b32_e32 v14, 16, v70
	v_and_b32_e32 v15, 0xffff0000, v70
	v_lshlrev_b32_e32 v18, 16, v71
	v_and_b32_e32 v19, 0xffff0000, v71
	v_pk_fma_f32 v[8:9], v[8:9], 0.5, v[14:15] op_sel_hi:[1,0,1]
	v_pk_fma_f32 v[10:11], v[10:11], 0.5, v[18:19] op_sel_hi:[1,0,1]
	v_cvt_pk_bf16_f32 v14, v8, v9
	v_mul_f32_e32 v9, v9, v9
	v_fmac_f32_e32 v9, v8, v8
	v_mul_f32_e32 v8, v11, v11
	v_fmac_f32_e32 v8, v10, v10
	v_add_f32_e32 v8, v9, v8
	v_add_f32_e32 v18, v20, v8
	v_lshl_add_u64 v[8:9], s[78:79], 0, v[94:95]
	v_lshl_add_u64 v[8:9], v[8:9], 0, s[34:35]
	v_lshl_add_u64 v[8:9], v[8:9], 0, s[14:15]
	v_cvt_pk_bf16_f32 v15, v10, v11
	v_lshl_add_u64 v[8:9], v[8:9], 0, v[200:201]
	global_store_dwordx4 v[8:9], v[12:15], off
	v_lshlrev_b32_e32 v10, 16, v64
	v_and_b32_e32 v11, 0xffff0000, v64
	v_lshlrev_b32_e32 v12, 16, v65
	v_and_b32_e32 v13, 0xffff0000, v65
	v_pk_fma_f32 v[6:7], v[6:7], 0.5, v[12:13] op_sel_hi:[1,0,1]
	v_pk_fma_f32 v[10:11], v[4:5], 0.5, v[10:11] op_sel_hi:[1,0,1]
	v_cvt_pk_bf16_f32 v5, v6, v7
	v_cvt_pk_bf16_f32 v4, v10, v11
	v_mul_f32_e32 v11, v11, v11
	v_mul_f32_e32 v7, v7, v7
	v_fmac_f32_e32 v11, v10, v10
	v_fmac_f32_e32 v7, v6, v6
	v_add_f32_e32 v6, v11, v7
	v_add_f32_e32 v12, v18, v6
	v_lshlrev_b32_e32 v6, 16, v66
	v_and_b32_e32 v7, 0xffff0000, v66
	v_lshlrev_b32_e32 v10, 16, v67
	v_and_b32_e32 v11, 0xffff0000, v67
	v_pk_fma_f32 v[0:1], v[0:1], 0.5, v[6:7] op_sel_hi:[1,0,1]
	v_pk_fma_f32 v[2:3], v[2:3], 0.5, v[10:11] op_sel_hi:[1,0,1]
	v_cvt_pk_bf16_f32 v6, v0, v1
	v_mul_f32_e32 v1, v1, v1
	v_fmac_f32_e32 v1, v0, v0
	v_mul_f32_e32 v0, v3, v3
	v_fmac_f32_e32 v0, v2, v2
	v_add_f32_e32 v48, v49, v48
	v_add_f32_e32 v32, v33, v32
	v_add_f32_e32 v16, v17, v16
	v_add_f32_e32 v0, v1, v0
	v_add_f32_e32 v48, v48, v60
	v_add_f32_e32 v32, v32, v44
	v_add_f32_e32 v16, v16, v28
	v_add_f32_e32 v0, v0, v12
	ds_bpermute_b32 v49, v167, v48
	ds_bpermute_b32 v33, v167, v32
	ds_bpermute_b32 v17, v167, v16
	ds_bpermute_b32 v1, v167, v0
	v_cvt_pk_bf16_f32 v7, v2, v3
	s_waitcnt lgkmcnt(3)
	v_add_f32_e32 v48, v48, v49
	s_waitcnt lgkmcnt(2)
	v_add_f32_e32 v32, v32, v33
	s_waitcnt lgkmcnt(1)
	v_add_f32_e32 v16, v16, v17
	s_waitcnt lgkmcnt(0)
	v_add_f32_e32 v0, v0, v1
	ds_bpermute_b32 v49, v166, v48
	ds_bpermute_b32 v33, v166, v32
	ds_bpermute_b32 v17, v166, v16
	ds_bpermute_b32 v1, v166, v0
	global_store_dwordx4 v[8:9], v[4:7], off offset:256
	s_and_saveexec_b64 s[34:35], s[2:3]
	s_cbranch_execz .LBB0_269
	s_waitcnt lgkmcnt(3)
	v_add_f32_e32 v3, v48, v49
	s_waitcnt lgkmcnt(0)
	v_add_f32_e32 v0, v0, v1
	v_add_f32_e32 v1, v16, v17
	v_add_f32_e32 v2, v32, v33
	global_atomic_add_f32 v[92:93], v3, off offset:512
	global_atomic_add_f32 v[92:93], v2, off offset:576
	global_atomic_add_f32 v[92:93], v1, off offset:640
	global_atomic_add_f32 v[92:93], v0, off offset:704

.LBB0_1555:
	s_mov_b32 s98, 0x40000
	s_mov_b32 s99, 0
	s_lshl_b32 s20, s18, 8
	s_lshl_b32 s18, s19, 8
	v_add_u32_e32 v162, s20, v170
	s_ashr_i32 s19, s18, 31
	s_lshl_b64 s[18:19], s[18:19], 1
	v_ashrrev_i32_e32 v163, 31, v162
	v_lshl_add_u64 v[164:165], v[150:151], 0, s[18:19]
	v_lshlrev_b64 v[128:129], 11, v[162:163]
	v_lshl_add_u64 v[130:131], v[164:165], 0, v[128:129]
	v_lshl_add_u64 v[222:223], v[130:131], 0, s[98:99]
	global_load_dwordx4 v[210:213], v[222:223], off
	global_load_dwordx4 v[214:217], v[222:223], off offset:256
	global_load_dwordx4 v[178:181], v[130:131], off
	global_load_dwordx4 v[182:185], v[130:131], off offset:256
	v_and_b32_e32 v131, 64, v175
	v_xor_b32_e32 v130, 16, v175
	v_add_u32_e32 v131, 64, v131
	v_cmp_lt_i32_e32 vcc, v130, v131
	v_xor_b32_e32 v132, 32, v175
	v_or_b32_e32 v134, 48, v162
	v_cndmask_b32_e32 v133, v175, v130, vcc
	v_or_b32_e32 v130, 16, v162
	v_cmp_lt_i32_e32 vcc, v132, v131
	v_ashrrev_i32_e32 v131, 31, v130
	v_lshlrev_b64 v[198:199], 11, v[130:131]
	v_lshl_add_u64 v[130:131], v[164:165], 0, v[198:199]
	v_lshl_add_u64 v[222:223], v[130:131], 0, s[98:99]
	global_load_dwordx4 v[218:221], v[222:223], off
	global_load_dwordx4 v[226:229], v[222:223], off offset:256
	global_load_dwordx4 v[186:189], v[130:131], off
	v_cndmask_b32_e32 v135, v175, v132, vcc
	v_or_b32_e32 v132, 32, v162
	v_lshlrev_b32_e32 v176, 2, v133
	v_ashrrev_i32_e32 v133, 31, v132
	v_lshlrev_b32_e32 v163, 2, v135
	v_ashrrev_i32_e32 v135, 31, v134
	v_lshlrev_b64 v[168:169], 11, v[132:133]
	v_lshlrev_b64 v[166:167], 11, v[134:135]
	v_lshl_add_u64 v[128:129], s[78:79], 0, v[128:129]
	v_lshl_add_u64 v[132:133], v[164:165], 0, v[168:169]
	v_lshl_add_u64 v[200:201], v[164:165], 0, v[166:167]
	v_lshl_add_u64 v[202:203], v[128:129], 0, s[18:19]
	global_load_dwordx4 v[190:193], v[130:131], off offset:256
	v_lshl_add_u64 v[222:223], v[132:133], 0, s[98:99]
	global_load_dwordx4 v[236:239], v[222:223], off
	global_load_dwordx4 v[240:243], v[222:223], off offset:256
	global_load_dwordx4 v[194:197], v[132:133], off
	global_load_dwordx4 v[136:139], v[132:133], off offset:256
	s_nop 0
	v_lshl_add_u64 v[222:223], v[200:201], 0, s[98:99]
	global_load_dwordx4 v[246:249], v[222:223], off
	global_load_dwordx4 v[250:253], v[222:223], off offset:256
	global_load_dwordx4 v[132:135], v[200:201], off
	global_load_dwordx4 v[128:131], v[200:201], off offset:256
	v_lshl_add_u64 v[200:201], v[202:203], 0, s[0:1]
	v_lshl_add_u64 v[200:201], v[200:201], 0, v[148:149]
	s_ashr_i32 s21, s20, 31
	s_waitcnt vmcnt(0)
	v_lshlrev_b32_e32 v202, 16, v178
	v_and_b32_e32 v203, 0xffff0000, v178
	v_lshlrev_b32_e32 v178, 16, v179
	v_and_b32_e32 v179, 0xffff0000, v179
	v_lshlrev_b32_e32 v204, 16, v180
	v_and_b32_e32 v205, 0xffff0000, v180
	v_lshlrev_b32_e32 v180, 16, v181
	v_and_b32_e32 v181, 0xffff0000, v181
	v_lshlrev_b32_e32 v206, 16, v182
	v_and_b32_e32 v207, 0xffff0000, v182
	v_lshlrev_b32_e32 v182, 16, v183
	v_and_b32_e32 v183, 0xffff0000, v183
	v_lshlrev_b32_e32 v208, 16, v184
	v_and_b32_e32 v209, 0xffff0000, v184
	v_lshlrev_b32_e32 v184, 16, v185
	v_and_b32_e32 v185, 0xffff0000, v185
	v_pk_add_f32 v[126:127], v[126:127], v[178:179]
	v_pk_add_f32 v[124:125], v[124:125], v[202:203]
	v_pk_add_f32 v[122:123], v[122:123], v[180:181]
	v_pk_add_f32 v[120:121], v[120:121], v[204:205]
	v_pk_add_f32 v[118:119], v[118:119], v[182:183]
	v_pk_add_f32 v[178:179], v[116:117], v[206:207]
	v_pk_add_f32 v[180:181], v[114:115], v[184:185]
	v_pk_add_f32 v[182:183], v[112:113], v[208:209]
	v_cvt_pk_bf16_f32 v112, v124, v125
	v_mul_f32_e32 v117, v125, v125
	v_mul_f32_e32 v125, v127, v127
	v_cvt_pk_bf16_f32 v114, v120, v121
	v_cvt_pk_bf16_f32 v115, v122, v123
	v_mul_f32_e32 v121, v121, v121
	v_mul_f32_e32 v123, v123, v123
	v_cvt_pk_bf16_f32 v113, v126, v127
	v_mul_f32_e32 v127, v179, v179
	v_mul_f32_e32 v177, v119, v119
	v_fmac_f32_e32 v117, v124, v124
	v_fmac_f32_e32 v125, v126, v126
	v_fmac_f32_e32 v121, v120, v120
	v_fmac_f32_e32 v123, v122, v122
	global_store_dwordx4 v[200:201], v[112:115], off
	v_fmac_f32_e32 v127, v178, v178
	v_fmac_f32_e32 v177, v118, v118
	v_add_f32_e32 v112, v117, v125
	v_add_f32_e32 v113, v121, v123
	v_cvt_pk_bf16_f32 v116, v178, v179
	v_add_f32_e32 v114, v127, v177
	v_add_f32_e32 v112, v112, v113
	v_cvt_pk_bf16_f32 v117, v118, v119
	v_cvt_pk_bf16_f32 v118, v182, v183
	v_cvt_pk_bf16_f32 v119, v180, v181
	v_add_f32_e32 v112, v112, v114
	global_store_dwordx4 v[200:201], v[116:119], off offset:256
	v_lshlrev_b32_e32 v114, 16, v186
	v_and_b32_e32 v115, 0xffff0000, v186
	v_lshlrev_b32_e32 v116, 16, v187
	v_and_b32_e32 v117, 0xffff0000, v187
	v_pk_add_f32 v[110:111], v[110:111], v[116:117]
	v_pk_add_f32 v[114:115], v[108:109], v[114:115]
	v_cvt_pk_bf16_f32 v109, v110, v111
	v_cvt_pk_bf16_f32 v108, v114, v115
	v_mul_f32_e32 v115, v115, v115
	v_mul_f32_e32 v111, v111, v111
	v_fmac_f32_e32 v115, v114, v114
	v_fmac_f32_e32 v111, v110, v110
	v_add_f32_e32 v116, v115, v111
	v_lshlrev_b32_e32 v110, 16, v188
	v_and_b32_e32 v111, 0xffff0000, v188
	v_lshlrev_b32_e32 v114, 16, v189
	v_and_b32_e32 v115, 0xffff0000, v189
	v_pk_add_f32 v[104:105], v[104:105], v[110:111]
	v_pk_add_f32 v[106:107], v[106:107], v[114:115]
	v_cvt_pk_bf16_f32 v110, v104, v105
	v_mul_f32_e32 v105, v105, v105
	v_fmac_f32_e32 v105, v104, v104
	v_mul_f32_e32 v104, v107, v107
	v_fmac_f32_e32 v104, v106, v106
	v_add_f32_e32 v104, v105, v104
	v_add_f32_e32 v114, v116, v104
	v_lshl_add_u64 v[104:105], s[78:79], 0, v[198:199]
	v_lshl_add_u64 v[104:105], v[104:105], 0, s[18:19]
	v_lshl_add_u64 v[104:105], v[104:105], 0, s[0:1]
	v_cvt_pk_bf16_f32 v111, v106, v107
	v_lshl_add_u64 v[104:105], v[104:105], 0, v[148:149]
	v_lshlrev_b32_e32 v106, 16, v190
	v_and_b32_e32 v107, 0xffff0000, v190
	global_store_dwordx4 v[104:105], v[108:111], off
	v_pk_add_f32 v[106:107], v[100:101], v[106:107]
	v_mul_f32_e32 v179, v183, v183
	v_lshlrev_b32_e32 v108, 16, v191
	v_and_b32_e32 v109, 0xffff0000, v191
	v_pk_add_f32 v[102:103], v[102:103], v[108:109]
	v_mul_f32_e32 v101, v107, v107
	v_cvt_pk_bf16_f32 v100, v106, v107
	v_fmac_f32_e32 v101, v106, v106
	v_mul_f32_e32 v106, v103, v103
	v_fmac_f32_e32 v106, v102, v102
	v_add_f32_e32 v101, v101, v106
	v_lshlrev_b32_e32 v106, 16, v192
	v_and_b32_e32 v107, 0xffff0000, v192
	v_lshlrev_b32_e32 v108, 16, v193
	v_and_b32_e32 v109, 0xffff0000, v193
	v_pk_add_f32 v[98:99], v[98:99], v[108:109]
	v_pk_add_f32 v[96:97], v[96:97], v[106:107]
	v_mul_f32_e32 v107, v99, v99
	v_mul_f32_e32 v106, v97, v97
	v_fmac_f32_e32 v106, v96, v96
	v_fmac_f32_e32 v107, v98, v98
	v_add_f32_e32 v101, v114, v101
	v_add_f32_e32 v106, v106, v107
	v_add_f32_e32 v106, v106, v101
	v_cvt_pk_bf16_f32 v101, v102, v103
	v_cvt_pk_bf16_f32 v102, v96, v97
	v_cvt_pk_bf16_f32 v103, v98, v99
	global_store_dwordx4 v[104:105], v[100:103], off offset:256
	v_lshlrev_b32_e32 v98, 16, v194
	v_and_b32_e32 v99, 0xffff0000, v194
	v_lshlrev_b32_e32 v100, 16, v195
	v_and_b32_e32 v101, 0xffff0000, v195
	v_pk_add_f32 v[94:95], v[94:95], v[100:101]
	v_pk_add_f32 v[98:99], v[92:93], v[98:99]
	v_cvt_pk_bf16_f32 v93, v94, v95
	v_cvt_pk_bf16_f32 v92, v98, v99
	v_mul_f32_e32 v99, v99, v99
	v_mul_f32_e32 v95, v95, v95
	v_fmac_f32_e32 v99, v98, v98
	v_fmac_f32_e32 v95, v94, v94
	v_add_f32_e32 v100, v99, v95
	v_lshlrev_b32_e32 v94, 16, v196
	v_and_b32_e32 v95, 0xffff0000, v196
	v_lshlrev_b32_e32 v98, 16, v197
	v_and_b32_e32 v99, 0xffff0000, v197
	v_pk_add_f32 v[88:89], v[88:89], v[94:95]
	v_pk_add_f32 v[90:91], v[90:91], v[98:99]
	v_cvt_pk_bf16_f32 v94, v88, v89
	v_mul_f32_e32 v89, v89, v89
	v_fmac_f32_e32 v89, v88, v88
	v_mul_f32_e32 v88, v91, v91
	v_fmac_f32_e32 v88, v90, v90
	v_add_f32_e32 v88, v89, v88
	v_add_f32_e32 v98, v100, v88
	v_lshl_add_u64 v[88:89], s[78:79], 0, v[168:169]
	v_lshl_add_u64 v[88:89], v[88:89], 0, s[18:19]
	v_lshl_add_u64 v[88:89], v[88:89], 0, s[0:1]
	v_cvt_pk_bf16_f32 v95, v90, v91
	v_lshl_add_u64 v[88:89], v[88:89], 0, v[148:149]
	v_lshlrev_b32_e32 v90, 16, v136
	v_and_b32_e32 v91, 0xffff0000, v136
	global_store_dwordx4 v[88:89], v[92:95], off
	v_pk_add_f32 v[90:91], v[84:85], v[90:91]
	v_mul_f32_e32 v113, v181, v181
	v_lshlrev_b32_e32 v92, 16, v137
	v_and_b32_e32 v93, 0xffff0000, v137
	v_pk_add_f32 v[86:87], v[86:87], v[92:93]
	v_mul_f32_e32 v85, v91, v91
	v_cvt_pk_bf16_f32 v84, v90, v91
	v_fmac_f32_e32 v85, v90, v90
	v_mul_f32_e32 v90, v87, v87
	v_fmac_f32_e32 v90, v86, v86
	v_add_f32_e32 v85, v85, v90
	v_lshlrev_b32_e32 v90, 16, v138
	v_and_b32_e32 v91, 0xffff0000, v138
	v_lshlrev_b32_e32 v92, 16, v139
	v_and_b32_e32 v93, 0xffff0000, v139
	v_pk_add_f32 v[82:83], v[82:83], v[92:93]
	v_pk_add_f32 v[80:81], v[80:81], v[90:91]
	v_mul_f32_e32 v91, v83, v83
	v_mul_f32_e32 v90, v81, v81
	v_fmac_f32_e32 v90, v80, v80
	v_fmac_f32_e32 v91, v82, v82
	v_add_f32_e32 v85, v98, v85
	v_add_f32_e32 v90, v90, v91
	v_add_f32_e32 v90, v90, v85
	v_cvt_pk_bf16_f32 v85, v86, v87
	v_cvt_pk_bf16_f32 v86, v80, v81
	v_cvt_pk_bf16_f32 v87, v82, v83
	global_store_dwordx4 v[88:89], v[84:87], off offset:256
	v_lshlrev_b32_e32 v82, 16, v132
	v_and_b32_e32 v83, 0xffff0000, v132
	v_lshlrev_b32_e32 v84, 16, v133
	v_and_b32_e32 v85, 0xffff0000, v133
	v_pk_add_f32 v[78:79], v[78:79], v[84:85]
	v_pk_add_f32 v[82:83], v[76:77], v[82:83]
	v_cvt_pk_bf16_f32 v77, v78, v79
	v_cvt_pk_bf16_f32 v76, v82, v83
	v_mul_f32_e32 v83, v83, v83
	v_mul_f32_e32 v79, v79, v79
	v_fmac_f32_e32 v83, v82, v82
	v_fmac_f32_e32 v79, v78, v78
	v_add_f32_e32 v84, v83, v79
	v_lshlrev_b32_e32 v78, 16, v134
	v_and_b32_e32 v79, 0xffff0000, v134
	v_lshlrev_b32_e32 v82, 16, v135
	v_and_b32_e32 v83, 0xffff0000, v135
	v_pk_add_f32 v[72:73], v[72:73], v[78:79]
	v_pk_add_f32 v[74:75], v[74:75], v[82:83]
	v_cvt_pk_bf16_f32 v78, v72, v73
	v_mul_f32_e32 v73, v73, v73
	v_fmac_f32_e32 v73, v72, v72
	v_mul_f32_e32 v72, v75, v75
	v_cvt_pk_bf16_f32 v79, v74, v75
	v_fmac_f32_e32 v72, v74, v74
	v_lshlrev_b32_e32 v74, 16, v128
	v_and_b32_e32 v75, 0xffff0000, v128
	v_lshlrev_b32_e32 v82, 16, v129
	v_and_b32_e32 v83, 0xffff0000, v129
	v_pk_add_f32 v[70:71], v[70:71], v[82:83]
	v_pk_add_f32 v[68:69], v[68:69], v[74:75]
	v_mul_f32_e32 v75, v71, v71
	v_mul_f32_e32 v74, v69, v69
	v_add_f32_e32 v72, v73, v72
	v_fmac_f32_e32 v74, v68, v68
	v_fmac_f32_e32 v75, v70, v70
	v_add_f32_e32 v84, v84, v72
	v_add_f32_e32 v74, v74, v75
	v_add_f32_e32 v84, v84, v74
	v_lshlrev_b32_e32 v74, 16, v130
	v_and_b32_e32 v75, 0xffff0000, v130
	v_lshlrev_b32_e32 v82, 16, v131
	v_and_b32_e32 v83, 0xffff0000, v131
	v_pk_add_f32 v[82:83], v[66:67], v[82:83]
	v_pk_add_f32 v[74:75], v[64:65], v[74:75]
	v_mul_f32_e32 v65, v83, v83
	v_mul_f32_e32 v64, v75, v75
	v_fmac_f32_e32 v179, v182, v182
	v_fmac_f32_e32 v113, v180, v180
	v_fmac_f32_e32 v64, v74, v74
	v_fmac_f32_e32 v65, v82, v82
	v_add_f32_e32 v113, v179, v113
	v_add_f32_e32 v64, v64, v65
	v_add_f32_e32 v112, v113, v112
	v_add_f32_e32 v64, v64, v84
	ds_bpermute_b32 v113, v176, v112
	ds_bpermute_b32 v107, v176, v106
	ds_bpermute_b32 v91, v176, v90
	ds_bpermute_b32 v65, v176, v64
	v_lshl_add_u64 v[72:73], s[78:79], 0, v[166:167]
	s_waitcnt lgkmcnt(3)
	v_add_f32_e32 v112, v112, v113
	s_waitcnt lgkmcnt(2)
	v_add_f32_e32 v96, v106, v107
	s_waitcnt lgkmcnt(1)
	v_add_f32_e32 v80, v90, v91
	s_waitcnt lgkmcnt(0)
	v_add_f32_e32 v64, v64, v65
	ds_bpermute_b32 v113, v163, v112
	ds_bpermute_b32 v97, v163, v96
	ds_bpermute_b32 v81, v163, v80
	ds_bpermute_b32 v65, v163, v64
	v_lshl_add_u64 v[72:73], v[72:73], 0, s[18:19]
	v_lshl_add_u64 v[72:73], v[72:73], 0, s[0:1]
	v_lshl_add_u64 v[72:73], v[72:73], 0, v[148:149]
	global_store_dwordx4 v[72:73], v[76:79], off
	v_cvt_pk_bf16_f32 v66, v68, v69
	v_cvt_pk_bf16_f32 v67, v70, v71
	v_cvt_pk_bf16_f32 v68, v74, v75
	v_cvt_pk_bf16_f32 v69, v82, v83
	v_lshl_add_u64 v[76:77], s[20:21], 2, v[152:153]
	global_store_dwordx4 v[72:73], v[66:69], off offset:256
	s_and_saveexec_b64 s[20:21], s[2:3]
	s_cbranch_execz .LBB0_1557
	s_waitcnt lgkmcnt(3)
	v_add_f32_e32 v67, v112, v113
	s_waitcnt lgkmcnt(0)
	v_add_f32_e32 v64, v64, v65
	v_add_f32_e32 v65, v80, v81
	v_add_f32_e32 v66, v96, v97
	global_atomic_add_f32 v[76:77], v67, off
	global_atomic_add_f32 v[76:77], v66, off offset:64
	global_atomic_add_f32 v[76:77], v65, off offset:128
	global_atomic_add_f32 v[76:77], v64, off offset:192
.LBB0_1557:
	s_or_b64 exec, exec, s[20:21]
	v_add_u32_e32 v64, 0x80, v162
	s_waitcnt lgkmcnt(0)
	v_ashrrev_i32_e32 v65, 31, v64
	v_lshlrev_b64 v[64:65], 11, v[64:65]
	v_lshl_add_u64 v[66:67], v[164:165], 0, v[64:65]
	v_mov_b32_e32 v82, v210
	v_mov_b32_e32 v83, v211
	v_mov_b32_e32 v84, v212
	v_mov_b32_e32 v85, v213
	v_mov_b32_e32 v86, v214
	v_mov_b32_e32 v87, v215
	v_mov_b32_e32 v88, v216
	v_mov_b32_e32 v89, v217
	v_add_u32_e32 v66, 0x90, v162
	v_ashrrev_i32_e32 v67, 31, v66
	v_lshlrev_b64 v[102:103], 11, v[66:67]
	v_lshl_add_u64 v[66:67], v[164:165], 0, v[102:103]
	v_mov_b32_e32 v90, v218
	v_mov_b32_e32 v91, v219
	v_mov_b32_e32 v92, v220
	v_mov_b32_e32 v93, v221
	v_add_u32_e32 v68, 0xa0, v162
	v_add_u32_e32 v70, 0xb0, v162
	v_ashrrev_i32_e32 v69, 31, v68
	v_ashrrev_i32_e32 v71, 31, v70
	v_lshlrev_b64 v[80:81], 11, v[68:69]
	v_lshlrev_b64 v[78:79], 11, v[70:71]
	v_lshl_add_u64 v[68:69], v[164:165], 0, v[80:81]
	v_lshl_add_u64 v[104:105], v[164:165], 0, v[78:79]
	v_lshl_add_u64 v[106:107], s[78:79], 0, v[64:65]
	v_mov_b32_e32 v94, v226
	v_mov_b32_e32 v95, v227
	v_mov_b32_e32 v96, v228
	v_mov_b32_e32 v97, v229
	v_mov_b32_e32 v98, v236
	v_mov_b32_e32 v99, v237
	v_mov_b32_e32 v100, v238
	v_mov_b32_e32 v101, v239
	v_mov_b32_e32 v72, v240
	v_mov_b32_e32 v73, v241
	v_mov_b32_e32 v74, v242
	v_mov_b32_e32 v75, v243
	s_nop 0
	v_mov_b32_e32 v68, v246
	v_mov_b32_e32 v69, v247
	v_mov_b32_e32 v70, v248
	v_mov_b32_e32 v71, v249
	v_mov_b32_e32 v64, v250
	v_mov_b32_e32 v65, v251
	v_mov_b32_e32 v66, v252
	v_mov_b32_e32 v67, v253
	v_lshl_add_u64 v[104:105], v[106:107], 0, s[18:19]
	v_lshl_add_u64 v[104:105], v[104:105], 0, s[0:1]
	v_lshl_add_u64 v[104:105], v[104:105], 0, v[148:149]
	v_lshlrev_b32_e32 v106, 16, v82
	v_and_b32_e32 v107, 0xffff0000, v82
	v_lshlrev_b32_e32 v82, 16, v83
	v_and_b32_e32 v83, 0xffff0000, v83
	v_lshlrev_b32_e32 v108, 16, v84
	v_and_b32_e32 v109, 0xffff0000, v84
	v_lshlrev_b32_e32 v84, 16, v85
	v_and_b32_e32 v85, 0xffff0000, v85
	v_lshlrev_b32_e32 v110, 16, v86
	v_and_b32_e32 v111, 0xffff0000, v86
	v_lshlrev_b32_e32 v86, 16, v87
	v_and_b32_e32 v87, 0xffff0000, v87
	v_lshlrev_b32_e32 v112, 16, v88
	v_and_b32_e32 v113, 0xffff0000, v88
	v_lshlrev_b32_e32 v88, 16, v89
	v_and_b32_e32 v89, 0xffff0000, v89
	v_pk_add_f32 v[62:63], v[62:63], v[82:83]
	v_pk_add_f32 v[60:61], v[60:61], v[106:107]
	v_pk_add_f32 v[58:59], v[58:59], v[84:85]
	v_pk_add_f32 v[56:57], v[56:57], v[108:109]
	v_lshlrev_b32_e32 v114, 16, v90
	v_and_b32_e32 v115, 0xffff0000, v90
	v_lshlrev_b32_e32 v90, 16, v91
	v_and_b32_e32 v91, 0xffff0000, v91
	v_pk_add_f32 v[82:83], v[50:51], v[86:87]
	v_pk_add_f32 v[84:85], v[48:49], v[110:111]
	v_pk_add_f32 v[86:87], v[46:47], v[88:89]
	v_pk_add_f32 v[88:89], v[44:45], v[112:113]
	v_cvt_pk_bf16_f32 v44, v60, v61
	v_cvt_pk_bf16_f32 v45, v62, v63
	v_cvt_pk_bf16_f32 v46, v56, v57
	v_cvt_pk_bf16_f32 v47, v58, v59
	v_pk_add_f32 v[54:55], v[54:55], v[90:91]
	v_cvt_pk_bf16_f32 v48, v84, v85
	v_cvt_pk_bf16_f32 v49, v82, v83
	v_cvt_pk_bf16_f32 v50, v88, v89
	v_cvt_pk_bf16_f32 v51, v86, v87
	global_store_dwordx4 v[104:105], v[44:47], off
	global_store_dwordx4 v[104:105], v[48:51], off offset:256
	v_pk_add_f32 v[90:91], v[52:53], v[114:115]
	v_lshlrev_b32_e32 v46, 16, v92
	v_and_b32_e32 v47, 0xffff0000, v92
	v_cvt_pk_bf16_f32 v53, v54, v55
	v_mul_f32_e32 v55, v55, v55
	v_lshlrev_b32_e32 v48, 16, v93
	v_and_b32_e32 v49, 0xffff0000, v93
	v_pk_add_f32 v[40:41], v[40:41], v[46:47]
	v_cvt_pk_bf16_f32 v52, v90, v91
	v_mul_f32_e32 v91, v91, v91
	v_fmac_f32_e32 v55, v54, v54
	v_pk_add_f32 v[42:43], v[42:43], v[48:49]
	v_cvt_pk_bf16_f32 v54, v40, v41
	v_mul_f32_e32 v41, v41, v41
	v_fmac_f32_e32 v91, v90, v90
	v_fmac_f32_e32 v41, v40, v40
	v_mul_f32_e32 v40, v43, v43
	v_add_f32_e32 v50, v91, v55
	v_cvt_pk_bf16_f32 v55, v42, v43
	v_fmac_f32_e32 v40, v42, v42
	v_lshlrev_b32_e32 v42, 16, v94
	v_and_b32_e32 v43, 0xffff0000, v94
	v_lshlrev_b32_e32 v46, 16, v95
	v_and_b32_e32 v47, 0xffff0000, v95
	v_pk_add_f32 v[42:43], v[36:37], v[42:43]
	v_pk_add_f32 v[38:39], v[38:39], v[46:47]
	v_mul_f32_e32 v37, v43, v43
	v_cvt_pk_bf16_f32 v36, v42, v43
	v_fmac_f32_e32 v37, v42, v42
	v_mul_f32_e32 v42, v39, v39
	v_fmac_f32_e32 v42, v38, v38
	v_add_f32_e32 v37, v37, v42
	v_lshlrev_b32_e32 v42, 16, v96
	v_and_b32_e32 v43, 0xffff0000, v96
	v_lshlrev_b32_e32 v46, 16, v97
	v_and_b32_e32 v47, 0xffff0000, v97
	v_add_f32_e32 v40, v41, v40
	v_pk_add_f32 v[34:35], v[34:35], v[46:47]
	v_pk_add_f32 v[32:33], v[32:33], v[42:43]
	v_add_f32_e32 v48, v50, v40
	v_lshl_add_u64 v[40:41], s[78:79], 0, v[102:103]
	v_mul_f32_e32 v42, v33, v33
	v_mul_f32_e32 v43, v35, v35
	v_lshl_add_u64 v[40:41], v[40:41], 0, s[18:19]
	v_fmac_f32_e32 v42, v32, v32
	v_fmac_f32_e32 v43, v34, v34
	v_lshl_add_u64 v[40:41], v[40:41], 0, s[0:1]
	v_add_f32_e32 v37, v48, v37
	v_add_f32_e32 v42, v42, v43
	v_lshl_add_u64 v[40:41], v[40:41], 0, v[148:149]
	v_add_f32_e32 v42, v42, v37
	v_cvt_pk_bf16_f32 v37, v38, v39
	v_cvt_pk_bf16_f32 v38, v32, v33
	v_cvt_pk_bf16_f32 v39, v34, v35
	global_store_dwordx4 v[40:41], v[36:39], off offset:256
	v_lshlrev_b32_e32 v34, 16, v98
	v_and_b32_e32 v35, 0xffff0000, v98
	v_lshlrev_b32_e32 v36, 16, v99
	v_and_b32_e32 v37, 0xffff0000, v99
	v_pk_add_f32 v[30:31], v[30:31], v[36:37]
	v_pk_add_f32 v[34:35], v[28:29], v[34:35]
	v_cvt_pk_bf16_f32 v29, v30, v31
	v_cvt_pk_bf16_f32 v28, v34, v35
	v_mul_f32_e32 v35, v35, v35
	v_mul_f32_e32 v31, v31, v31
	v_fmac_f32_e32 v35, v34, v34
	v_fmac_f32_e32 v31, v30, v30
	v_add_f32_e32 v36, v35, v31
	v_lshlrev_b32_e32 v30, 16, v100
	v_and_b32_e32 v31, 0xffff0000, v100
	v_lshlrev_b32_e32 v34, 16, v101
	v_and_b32_e32 v35, 0xffff0000, v101
	v_pk_add_f32 v[24:25], v[24:25], v[30:31]
	v_pk_add_f32 v[26:27], v[26:27], v[34:35]
	v_cvt_pk_bf16_f32 v30, v24, v25
	v_mul_f32_e32 v25, v25, v25
	v_fmac_f32_e32 v25, v24, v24
	v_mul_f32_e32 v24, v27, v27
	v_fmac_f32_e32 v24, v26, v26
	v_add_f32_e32 v24, v25, v24
	v_add_f32_e32 v34, v36, v24
	v_lshl_add_u64 v[24:25], s[78:79], 0, v[80:81]
	v_lshl_add_u64 v[24:25], v[24:25], 0, s[18:19]
	v_lshl_add_u64 v[24:25], v[24:25], 0, s[0:1]
	v_cvt_pk_bf16_f32 v31, v26, v27
	v_lshl_add_u64 v[24:25], v[24:25], 0, v[148:149]
	v_lshlrev_b32_e32 v26, 16, v72
	v_and_b32_e32 v27, 0xffff0000, v72
	global_store_dwordx4 v[24:25], v[28:31], off
	v_pk_add_f32 v[26:27], v[20:21], v[26:27]
	v_mul_f32_e32 v61, v61, v61
	v_lshlrev_b32_e32 v28, 16, v73
	v_and_b32_e32 v29, 0xffff0000, v73
	v_pk_add_f32 v[22:23], v[22:23], v[28:29]
	v_mul_f32_e32 v21, v27, v27
	v_cvt_pk_bf16_f32 v20, v26, v27
	v_fmac_f32_e32 v21, v26, v26
	v_mul_f32_e32 v26, v23, v23
	v_fmac_f32_e32 v26, v22, v22
	v_add_f32_e32 v21, v21, v26
	v_lshlrev_b32_e32 v26, 16, v74
	v_and_b32_e32 v27, 0xffff0000, v74
	v_lshlrev_b32_e32 v28, 16, v75
	v_and_b32_e32 v29, 0xffff0000, v75
	v_pk_add_f32 v[18:19], v[18:19], v[28:29]
	v_pk_add_f32 v[16:17], v[16:17], v[26:27]
	v_mul_f32_e32 v27, v19, v19
	v_mul_f32_e32 v26, v17, v17
	v_fmac_f32_e32 v26, v16, v16
	v_fmac_f32_e32 v27, v18, v18
	v_add_f32_e32 v21, v34, v21
	v_add_f32_e32 v26, v26, v27
	v_add_f32_e32 v26, v26, v21
	v_cvt_pk_bf16_f32 v21, v22, v23
	v_cvt_pk_bf16_f32 v22, v16, v17
	v_cvt_pk_bf16_f32 v23, v18, v19
	global_store_dwordx4 v[24:25], v[20:23], off offset:256
	v_lshlrev_b32_e32 v18, 16, v68
	v_and_b32_e32 v19, 0xffff0000, v68
	v_lshlrev_b32_e32 v20, 16, v69
	v_and_b32_e32 v21, 0xffff0000, v69
	v_pk_add_f32 v[14:15], v[14:15], v[20:21]
	v_pk_add_f32 v[18:19], v[12:13], v[18:19]
	v_cvt_pk_bf16_f32 v13, v14, v15
	v_cvt_pk_bf16_f32 v12, v18, v19
	v_mul_f32_e32 v19, v19, v19
	v_mul_f32_e32 v15, v15, v15
	v_fmac_f32_e32 v19, v18, v18
	v_fmac_f32_e32 v15, v14, v14
	v_add_f32_e32 v20, v19, v15
	v_lshlrev_b32_e32 v14, 16, v70
	v_and_b32_e32 v15, 0xffff0000, v70
	v_lshlrev_b32_e32 v18, 16, v71
	v_and_b32_e32 v19, 0xffff0000, v71
	v_pk_add_f32 v[8:9], v[8:9], v[14:15]
	v_pk_add_f32 v[10:11], v[10:11], v[18:19]
	v_cvt_pk_bf16_f32 v14, v8, v9
	v_mul_f32_e32 v9, v9, v9
	v_fmac_f32_e32 v9, v8, v8
	v_mul_f32_e32 v8, v11, v11
	v_cvt_pk_bf16_f32 v15, v10, v11
	v_fmac_f32_e32 v8, v10, v10
	v_lshlrev_b32_e32 v10, 16, v64
	v_and_b32_e32 v11, 0xffff0000, v64
	v_lshlrev_b32_e32 v18, 16, v65
	v_and_b32_e32 v19, 0xffff0000, v65
	v_pk_add_f32 v[6:7], v[6:7], v[18:19]
	v_pk_add_f32 v[4:5], v[4:5], v[10:11]
	v_mul_f32_e32 v11, v7, v7
	v_mul_f32_e32 v10, v5, v5
	v_add_f32_e32 v8, v9, v8
	v_fmac_f32_e32 v10, v4, v4
	v_fmac_f32_e32 v11, v6, v6
	v_add_f32_e32 v20, v20, v8
	v_add_f32_e32 v10, v10, v11
	v_mul_f32_e32 v63, v63, v63
	v_mul_f32_e32 v57, v57, v57
	v_mul_f32_e32 v59, v59, v59
	v_add_f32_e32 v20, v20, v10
	v_lshlrev_b32_e32 v10, 16, v66
	v_and_b32_e32 v11, 0xffff0000, v66
	v_lshlrev_b32_e32 v18, 16, v67
	v_and_b32_e32 v19, 0xffff0000, v67
	v_mul_f32_e32 v85, v85, v85
	v_mul_f32_e32 v83, v83, v83
	v_fmac_f32_e32 v61, v60, v60
	v_fmac_f32_e32 v63, v62, v62
	v_fmac_f32_e32 v57, v56, v56
	v_fmac_f32_e32 v59, v58, v58
	v_pk_add_f32 v[18:19], v[2:3], v[18:19]
	v_pk_add_f32 v[10:11], v[0:1], v[10:11]
	v_mul_f32_e32 v89, v89, v89
	v_mul_f32_e32 v87, v87, v87
	v_fmac_f32_e32 v85, v84, v84
	v_fmac_f32_e32 v83, v82, v82
	v_add_f32_e32 v56, v61, v63
	v_add_f32_e32 v57, v57, v59
	v_mul_f32_e32 v0, v11, v11
	v_mul_f32_e32 v1, v19, v19
	v_fmac_f32_e32 v89, v88, v88
	v_fmac_f32_e32 v87, v86, v86
	v_add_f32_e32 v58, v85, v83
	v_add_f32_e32 v56, v56, v57
	v_fmac_f32_e32 v0, v10, v10
	v_fmac_f32_e32 v1, v18, v18
	v_add_f32_e32 v59, v89, v87
	v_add_f32_e32 v56, v56, v58
	v_add_f32_e32 v0, v0, v1
	v_add_f32_e32 v56, v59, v56
	v_add_f32_e32 v3, v0, v20
	ds_bpermute_b32 v57, v176, v56
	ds_bpermute_b32 v43, v176, v42
	ds_bpermute_b32 v27, v176, v26
	ds_bpermute_b32 v20, v176, v3
	v_lshl_add_u64 v[8:9], s[78:79], 0, v[78:79]
	v_lshl_add_u64 v[8:9], v[8:9], 0, s[18:19]
	v_lshl_add_u64 v[0:1], v[8:9], 0, s[0:1]
	s_waitcnt lgkmcnt(3)
	v_add_f32_e32 v44, v56, v57
	s_waitcnt lgkmcnt(2)
	v_add_f32_e32 v32, v42, v43
	s_waitcnt lgkmcnt(1)
	v_add_f32_e32 v16, v26, v27
	v_lshl_add_u64 v[8:9], v[0:1], 0, v[148:149]
	s_waitcnt lgkmcnt(0)
	v_add_f32_e32 v0, v3, v20
	ds_bpermute_b32 v45, v163, v44
	ds_bpermute_b32 v33, v163, v32
	ds_bpermute_b32 v17, v163, v16
	ds_bpermute_b32 v1, v163, v0
	v_cvt_pk_bf16_f32 v2, v4, v5
	v_cvt_pk_bf16_f32 v3, v6, v7
	v_cvt_pk_bf16_f32 v4, v10, v11
	v_cvt_pk_bf16_f32 v5, v18, v19
	global_store_dwordx4 v[40:41], v[52:55], off
	global_store_dwordx4 v[8:9], v[12:15], off
	global_store_dwordx4 v[8:9], v[2:5], off offset:256
	s_and_saveexec_b64 s[18:19], s[2:3]
	s_cbranch_execz .LBB0_1559
	s_waitcnt lgkmcnt(3)
	v_add_f32_e32 v3, v44, v45
	s_waitcnt lgkmcnt(0)
	v_add_f32_e32 v0, v0, v1
	v_add_f32_e32 v1, v16, v17
	v_add_f32_e32 v2, v32, v33
	global_atomic_add_f32 v[76:77], v3, off offset:512
	global_atomic_add_f32 v[76:77], v2, off offset:576
	global_atomic_add_f32 v[76:77], v1, off offset:640
	global_atomic_add_f32 v[76:77], v0, off offset:704

.LBB0_1719:
	s_mov_b32 s98, 0x40000
	s_mov_b32 s99, 0
	s_lshl_b32 s22, s53, 8
	s_lshl_b32 s20, s15, 8
	v_add_u32_e32 v140, s22, v225
	s_ashr_i32 s21, s20, 31
	s_lshl_b64 s[20:21], s[20:21], 1
	v_ashrrev_i32_e32 v141, 31, v140
	v_lshl_add_u64 v[142:143], v[204:205], 0, s[20:21]
	v_lshlrev_b64 v[128:129], 11, v[140:141]
	v_lshl_add_u64 v[130:131], v[142:143], 0, v[128:129]
	v_lshl_add_u64 v[190:191], v[130:131], 0, s[98:99]
	global_load_dwordx4 v[182:185], v[190:191], off
	global_load_dwordx4 v[186:189], v[190:191], off offset:256
	global_load_dwordx4 v[150:153], v[130:131], off
	global_load_dwordx4 v[154:157], v[130:131], off offset:256
	v_and_b32_e32 v131, 64, v230
	v_xor_b32_e32 v130, 16, v230
	v_add_u32_e32 v131, 64, v131
	v_cmp_lt_i32_e32 vcc, v130, v131
	v_xor_b32_e32 v132, 32, v230
	v_or_b32_e32 v134, 48, v140
	v_cndmask_b32_e32 v133, v230, v130, vcc
	v_or_b32_e32 v130, 16, v140
	v_cmp_lt_i32_e32 vcc, v132, v131
	v_ashrrev_i32_e32 v131, 31, v130
	v_lshlrev_b64 v[170:171], 11, v[130:131]
	v_lshl_add_u64 v[130:131], v[142:143], 0, v[170:171]
	v_lshl_add_u64 v[190:191], v[130:131], 0, s[98:99]
	global_load_dwordx4 v[216:219], v[190:191], off
	global_load_dwordx4 v[220:223], v[190:191], off offset:256
	global_load_dwordx4 v[158:161], v[130:131], off
	v_cndmask_b32_e32 v135, v230, v132, vcc
	v_or_b32_e32 v132, 32, v140
	v_lshlrev_b32_e32 v148, 2, v133
	v_ashrrev_i32_e32 v133, 31, v132
	v_lshlrev_b32_e32 v141, 2, v135
	v_ashrrev_i32_e32 v135, 31, v134
	v_lshlrev_b64 v[146:147], 11, v[132:133]
	v_lshlrev_b64 v[144:145], 11, v[134:135]
	v_lshl_add_u64 v[128:129], s[78:79], 0, v[128:129]
	v_lshl_add_u64 v[132:133], v[142:143], 0, v[146:147]
	v_lshl_add_u64 v[172:173], v[142:143], 0, v[144:145]
	v_lshl_add_u64 v[174:175], v[128:129], 0, s[20:21]
	global_load_dwordx4 v[162:165], v[130:131], off offset:256
	v_lshl_add_u64 v[190:191], v[132:133], 0, s[98:99]
	global_load_dwordx4 v[236:239], v[190:191], off
	global_load_dwordx4 v[240:243], v[190:191], off offset:256
	global_load_dwordx4 v[166:169], v[132:133], off
	global_load_dwordx4 v[136:139], v[132:133], off offset:256
	s_nop 0
	v_lshl_add_u64 v[190:191], v[172:173], 0, s[98:99]
	global_load_dwordx4 v[246:249], v[190:191], off
	global_load_dwordx4 v[250:253], v[190:191], off offset:256
	global_load_dwordx4 v[132:135], v[172:173], off
	global_load_dwordx4 v[128:131], v[172:173], off offset:256
	s_mov_b32 s15, s1
	v_lshl_add_u64 v[172:173], v[174:175], 0, s[14:15]
	v_lshl_add_u64 v[172:173], v[172:173], 0, v[200:201]
	s_ashr_i32 s23, s22, 31
	s_waitcnt vmcnt(0)
	v_lshlrev_b32_e32 v174, 16, v150
	v_and_b32_e32 v175, 0xffff0000, v150
	v_lshlrev_b32_e32 v150, 16, v151
	v_and_b32_e32 v151, 0xffff0000, v151
	v_lshlrev_b32_e32 v176, 16, v152
	v_and_b32_e32 v177, 0xffff0000, v152
	v_lshlrev_b32_e32 v152, 16, v153
	v_and_b32_e32 v153, 0xffff0000, v153
	v_lshlrev_b32_e32 v178, 16, v154
	v_and_b32_e32 v179, 0xffff0000, v154
	v_lshlrev_b32_e32 v154, 16, v155
	v_and_b32_e32 v155, 0xffff0000, v155
	v_lshlrev_b32_e32 v180, 16, v156
	v_and_b32_e32 v181, 0xffff0000, v156
	v_lshlrev_b32_e32 v156, 16, v157
	v_and_b32_e32 v157, 0xffff0000, v157
	v_pk_fma_f32 v[126:127], v[126:127], 0.5, v[150:151] op_sel_hi:[1,0,1]
	v_pk_fma_f32 v[124:125], v[124:125], 0.5, v[174:175] op_sel_hi:[1,0,1]
	v_pk_fma_f32 v[122:123], v[122:123], 0.5, v[152:153] op_sel_hi:[1,0,1]
	v_pk_fma_f32 v[120:121], v[120:121], 0.5, v[176:177] op_sel_hi:[1,0,1]
	v_pk_fma_f32 v[118:119], v[118:119], 0.5, v[154:155] op_sel_hi:[1,0,1]
	v_pk_fma_f32 v[150:151], v[116:117], 0.5, v[178:179] op_sel_hi:[1,0,1]
	v_pk_fma_f32 v[152:153], v[114:115], 0.5, v[156:157] op_sel_hi:[1,0,1]
	v_pk_fma_f32 v[154:155], v[112:113], 0.5, v[180:181] op_sel_hi:[1,0,1]
	v_cvt_pk_bf16_f32 v112, v124, v125
	v_mul_f32_e32 v117, v125, v125
	v_mul_f32_e32 v125, v127, v127
	v_cvt_pk_bf16_f32 v114, v120, v121
	v_cvt_pk_bf16_f32 v115, v122, v123
	v_mul_f32_e32 v121, v121, v121
	v_mul_f32_e32 v123, v123, v123
	v_cvt_pk_bf16_f32 v113, v126, v127
	v_mul_f32_e32 v127, v151, v151
	v_mul_f32_e32 v149, v119, v119
	v_fmac_f32_e32 v117, v124, v124
	v_fmac_f32_e32 v125, v126, v126
	v_fmac_f32_e32 v121, v120, v120
	v_fmac_f32_e32 v123, v122, v122
	global_store_dwordx4 v[172:173], v[112:115], off
	v_fmac_f32_e32 v127, v150, v150
	v_fmac_f32_e32 v149, v118, v118
	v_add_f32_e32 v112, v117, v125
	v_add_f32_e32 v113, v121, v123
	v_add_f32_e32 v114, v127, v149
	v_add_f32_e32 v112, v112, v113
	v_add_f32_e32 v112, v112, v114
	v_mul_f32_e32 v113, v155, v155
	v_mul_f32_e32 v114, v153, v153
	v_cvt_pk_bf16_f32 v116, v150, v151
	v_fmac_f32_e32 v113, v154, v154
	v_fmac_f32_e32 v114, v152, v152
	v_cvt_pk_bf16_f32 v117, v118, v119
	v_cvt_pk_bf16_f32 v118, v154, v155
	v_cvt_pk_bf16_f32 v119, v152, v153
	v_add_f32_e32 v113, v113, v114
	global_store_dwordx4 v[172:173], v[116:119], off offset:256
	v_lshlrev_b32_e32 v114, 16, v158
	v_and_b32_e32 v115, 0xffff0000, v158
	v_lshlrev_b32_e32 v116, 16, v159
	v_and_b32_e32 v117, 0xffff0000, v159
	v_pk_fma_f32 v[110:111], v[110:111], 0.5, v[116:117] op_sel_hi:[1,0,1]
	v_pk_fma_f32 v[114:115], v[108:109], 0.5, v[114:115] op_sel_hi:[1,0,1]
	v_cvt_pk_bf16_f32 v109, v110, v111
	v_cvt_pk_bf16_f32 v108, v114, v115
	v_mul_f32_e32 v115, v115, v115
	v_mul_f32_e32 v111, v111, v111
	v_fmac_f32_e32 v115, v114, v114
	v_fmac_f32_e32 v111, v110, v110
	v_add_f32_e32 v116, v115, v111
	v_lshlrev_b32_e32 v110, 16, v160
	v_and_b32_e32 v111, 0xffff0000, v160
	v_lshlrev_b32_e32 v114, 16, v161
	v_and_b32_e32 v115, 0xffff0000, v161
	v_pk_fma_f32 v[104:105], v[104:105], 0.5, v[110:111] op_sel_hi:[1,0,1]
	v_pk_fma_f32 v[106:107], v[106:107], 0.5, v[114:115] op_sel_hi:[1,0,1]
	v_cvt_pk_bf16_f32 v110, v104, v105
	v_mul_f32_e32 v105, v105, v105
	v_fmac_f32_e32 v105, v104, v104
	v_mul_f32_e32 v104, v107, v107
	v_fmac_f32_e32 v104, v106, v106
	v_add_f32_e32 v104, v105, v104
	v_add_f32_e32 v114, v116, v104
	v_lshl_add_u64 v[104:105], s[78:79], 0, v[170:171]
	v_lshl_add_u64 v[104:105], v[104:105], 0, s[20:21]
	v_lshl_add_u64 v[104:105], v[104:105], 0, s[14:15]
	v_cvt_pk_bf16_f32 v111, v106, v107
	v_lshl_add_u64 v[104:105], v[104:105], 0, v[200:201]
	v_lshlrev_b32_e32 v106, 16, v162
	v_and_b32_e32 v107, 0xffff0000, v162
	global_store_dwordx4 v[104:105], v[108:111], off
	v_pk_fma_f32 v[106:107], v[100:101], 0.5, v[106:107] op_sel_hi:[1,0,1]
	v_add_f32_e32 v112, v113, v112
	v_lshlrev_b32_e32 v108, 16, v163
	v_and_b32_e32 v109, 0xffff0000, v163
	v_pk_fma_f32 v[102:103], v[102:103], 0.5, v[108:109] op_sel_hi:[1,0,1]
	v_mul_f32_e32 v101, v107, v107
	v_cvt_pk_bf16_f32 v100, v106, v107
	v_fmac_f32_e32 v101, v106, v106
	v_mul_f32_e32 v106, v103, v103
	v_fmac_f32_e32 v106, v102, v102
	v_add_f32_e32 v101, v101, v106
	v_lshlrev_b32_e32 v106, 16, v164
	v_and_b32_e32 v107, 0xffff0000, v164
	v_lshlrev_b32_e32 v108, 16, v165
	v_and_b32_e32 v109, 0xffff0000, v165
	v_pk_fma_f32 v[98:99], v[98:99], 0.5, v[108:109] op_sel_hi:[1,0,1]
	v_pk_fma_f32 v[96:97], v[96:97], 0.5, v[106:107] op_sel_hi:[1,0,1]
	v_mul_f32_e32 v107, v99, v99
	v_mul_f32_e32 v106, v97, v97
	v_fmac_f32_e32 v106, v96, v96
	v_fmac_f32_e32 v107, v98, v98
	v_add_f32_e32 v101, v114, v101
	v_add_f32_e32 v106, v106, v107
	v_add_f32_e32 v106, v106, v101
	v_cvt_pk_bf16_f32 v101, v102, v103
	v_cvt_pk_bf16_f32 v102, v96, v97
	v_cvt_pk_bf16_f32 v103, v98, v99
	global_store_dwordx4 v[104:105], v[100:103], off offset:256
	v_lshlrev_b32_e32 v98, 16, v166
	v_and_b32_e32 v99, 0xffff0000, v166
	v_lshlrev_b32_e32 v100, 16, v167
	v_and_b32_e32 v101, 0xffff0000, v167
	v_pk_fma_f32 v[94:95], v[94:95], 0.5, v[100:101] op_sel_hi:[1,0,1]
	v_pk_fma_f32 v[98:99], v[92:93], 0.5, v[98:99] op_sel_hi:[1,0,1]
	v_cvt_pk_bf16_f32 v93, v94, v95
	v_cvt_pk_bf16_f32 v92, v98, v99
	v_mul_f32_e32 v99, v99, v99
	v_mul_f32_e32 v95, v95, v95
	v_fmac_f32_e32 v99, v98, v98
	v_fmac_f32_e32 v95, v94, v94
	v_add_f32_e32 v100, v99, v95
	v_lshlrev_b32_e32 v94, 16, v168
	v_and_b32_e32 v95, 0xffff0000, v168
	v_lshlrev_b32_e32 v98, 16, v169
	v_and_b32_e32 v99, 0xffff0000, v169
	v_pk_fma_f32 v[88:89], v[88:89], 0.5, v[94:95] op_sel_hi:[1,0,1]
	v_pk_fma_f32 v[90:91], v[90:91], 0.5, v[98:99] op_sel_hi:[1,0,1]
	v_cvt_pk_bf16_f32 v94, v88, v89
	v_mul_f32_e32 v89, v89, v89
	v_fmac_f32_e32 v89, v88, v88
	v_mul_f32_e32 v88, v91, v91
	v_fmac_f32_e32 v88, v90, v90
	v_add_f32_e32 v88, v89, v88
	v_add_f32_e32 v98, v100, v88
	v_lshl_add_u64 v[88:89], s[78:79], 0, v[146:147]
	v_lshl_add_u64 v[88:89], v[88:89], 0, s[20:21]
	v_lshl_add_u64 v[88:89], v[88:89], 0, s[14:15]
	v_cvt_pk_bf16_f32 v95, v90, v91
	v_lshl_add_u64 v[88:89], v[88:89], 0, v[200:201]
	v_lshlrev_b32_e32 v90, 16, v136
	v_and_b32_e32 v91, 0xffff0000, v136
	global_store_dwordx4 v[88:89], v[92:95], off
	v_pk_fma_f32 v[90:91], v[84:85], 0.5, v[90:91] op_sel_hi:[1,0,1]
	ds_bpermute_b32 v113, v148, v112
	v_lshlrev_b32_e32 v92, 16, v137
	v_and_b32_e32 v93, 0xffff0000, v137
	v_pk_fma_f32 v[86:87], v[86:87], 0.5, v[92:93] op_sel_hi:[1,0,1]
	v_mul_f32_e32 v85, v91, v91
	v_cvt_pk_bf16_f32 v84, v90, v91
	v_fmac_f32_e32 v85, v90, v90
	v_mul_f32_e32 v90, v87, v87
	v_fmac_f32_e32 v90, v86, v86
	v_add_f32_e32 v85, v85, v90
	v_lshlrev_b32_e32 v90, 16, v138
	v_and_b32_e32 v91, 0xffff0000, v138
	v_lshlrev_b32_e32 v92, 16, v139
	v_and_b32_e32 v93, 0xffff0000, v139
	v_pk_fma_f32 v[82:83], v[82:83], 0.5, v[92:93] op_sel_hi:[1,0,1]
	v_pk_fma_f32 v[80:81], v[80:81], 0.5, v[90:91] op_sel_hi:[1,0,1]
	v_mul_f32_e32 v91, v83, v83
	v_mul_f32_e32 v90, v81, v81
	v_fmac_f32_e32 v90, v80, v80
	v_fmac_f32_e32 v91, v82, v82
	v_add_f32_e32 v85, v98, v85
	v_add_f32_e32 v90, v90, v91
	v_add_f32_e32 v90, v90, v85
	v_cvt_pk_bf16_f32 v85, v86, v87
	v_cvt_pk_bf16_f32 v86, v80, v81
	v_cvt_pk_bf16_f32 v87, v82, v83
	global_store_dwordx4 v[88:89], v[84:87], off offset:256
	v_lshlrev_b32_e32 v82, 16, v132
	v_and_b32_e32 v83, 0xffff0000, v132
	v_lshlrev_b32_e32 v84, 16, v133
	v_and_b32_e32 v85, 0xffff0000, v133
	v_pk_fma_f32 v[78:79], v[78:79], 0.5, v[84:85] op_sel_hi:[1,0,1]
	v_pk_fma_f32 v[82:83], v[76:77], 0.5, v[82:83] op_sel_hi:[1,0,1]
	v_cvt_pk_bf16_f32 v77, v78, v79
	v_cvt_pk_bf16_f32 v76, v82, v83
	v_mul_f32_e32 v83, v83, v83
	v_mul_f32_e32 v79, v79, v79
	v_fmac_f32_e32 v83, v82, v82
	v_fmac_f32_e32 v79, v78, v78
	v_add_f32_e32 v84, v83, v79
	v_lshlrev_b32_e32 v78, 16, v134
	v_and_b32_e32 v79, 0xffff0000, v134
	v_lshlrev_b32_e32 v82, 16, v135
	v_and_b32_e32 v83, 0xffff0000, v135
	v_pk_fma_f32 v[72:73], v[72:73], 0.5, v[78:79] op_sel_hi:[1,0,1]
	v_pk_fma_f32 v[74:75], v[74:75], 0.5, v[82:83] op_sel_hi:[1,0,1]
	v_cvt_pk_bf16_f32 v78, v72, v73
	v_mul_f32_e32 v73, v73, v73
	v_fmac_f32_e32 v73, v72, v72
	v_mul_f32_e32 v72, v75, v75
	v_cvt_pk_bf16_f32 v79, v74, v75
	v_fmac_f32_e32 v72, v74, v74
	v_lshlrev_b32_e32 v74, 16, v128
	v_and_b32_e32 v75, 0xffff0000, v128
	v_lshlrev_b32_e32 v82, 16, v129
	v_and_b32_e32 v83, 0xffff0000, v129
	v_pk_fma_f32 v[70:71], v[70:71], 0.5, v[82:83] op_sel_hi:[1,0,1]
	v_pk_fma_f32 v[68:69], v[68:69], 0.5, v[74:75] op_sel_hi:[1,0,1]
	v_mul_f32_e32 v75, v71, v71
	v_mul_f32_e32 v74, v69, v69
	v_add_f32_e32 v72, v73, v72
	v_fmac_f32_e32 v74, v68, v68
	v_fmac_f32_e32 v75, v70, v70
	v_add_f32_e32 v84, v84, v72
	v_add_f32_e32 v74, v74, v75
	v_add_f32_e32 v84, v84, v74
	v_lshlrev_b32_e32 v74, 16, v130
	v_and_b32_e32 v75, 0xffff0000, v130
	v_lshlrev_b32_e32 v82, 16, v131
	v_and_b32_e32 v83, 0xffff0000, v131
	v_pk_fma_f32 v[82:83], v[66:67], 0.5, v[82:83] op_sel_hi:[1,0,1]
	v_pk_fma_f32 v[74:75], v[64:65], 0.5, v[74:75] op_sel_hi:[1,0,1]
	v_mul_f32_e32 v65, v83, v83
	v_mul_f32_e32 v64, v75, v75
	v_fmac_f32_e32 v64, v74, v74
	v_fmac_f32_e32 v65, v82, v82
	v_add_f32_e32 v64, v64, v65
	v_add_f32_e32 v64, v64, v84
	ds_bpermute_b32 v107, v148, v106
	ds_bpermute_b32 v91, v148, v90
	ds_bpermute_b32 v65, v148, v64
	s_waitcnt lgkmcnt(3)
	v_add_f32_e32 v112, v112, v113
	ds_bpermute_b32 v113, v141, v112
	s_waitcnt lgkmcnt(3)
	v_add_f32_e32 v96, v106, v107
	s_waitcnt lgkmcnt(2)
	v_add_f32_e32 v80, v90, v91
	s_waitcnt lgkmcnt(1)
	v_add_f32_e32 v64, v64, v65
	ds_bpermute_b32 v97, v141, v96
	ds_bpermute_b32 v81, v141, v80
	v_lshl_add_u64 v[72:73], s[78:79], 0, v[144:145]
	ds_bpermute_b32 v65, v141, v64
	v_lshl_add_u64 v[72:73], v[72:73], 0, s[20:21]
	v_lshl_add_u64 v[72:73], v[72:73], 0, s[14:15]
	v_lshl_add_u64 v[72:73], v[72:73], 0, v[200:201]
	global_store_dwordx4 v[72:73], v[76:79], off
	v_cvt_pk_bf16_f32 v66, v68, v69
	v_cvt_pk_bf16_f32 v67, v70, v71
	v_cvt_pk_bf16_f32 v68, v74, v75
	v_cvt_pk_bf16_f32 v69, v82, v83
	v_lshl_add_u64 v[76:77], s[22:23], 2, v[206:207]
	global_store_dwordx4 v[72:73], v[66:69], off offset:256
	s_and_saveexec_b64 s[22:23], s[2:3]
	s_cbranch_execz .LBB0_1721
	s_waitcnt lgkmcnt(3)
	v_add_f32_e32 v67, v112, v113
	s_waitcnt lgkmcnt(0)
	v_add_f32_e32 v64, v64, v65
	v_add_f32_e32 v65, v80, v81
	v_add_f32_e32 v66, v96, v97
	global_atomic_add_f32 v[76:77], v67, off
	global_atomic_add_f32 v[76:77], v66, off offset:64
	global_atomic_add_f32 v[76:77], v65, off offset:128
	global_atomic_add_f32 v[76:77], v64, off offset:192
.LBB0_1721:
	s_or_b64 exec, exec, s[22:23]
	v_add_u32_e32 v64, 0x80, v140
	s_waitcnt lgkmcnt(0)
	v_ashrrev_i32_e32 v65, 31, v64
	v_lshlrev_b64 v[64:65], 11, v[64:65]
	v_lshl_add_u64 v[66:67], v[142:143], 0, v[64:65]
	v_mov_b32_e32 v82, v182
	v_mov_b32_e32 v83, v183
	v_mov_b32_e32 v84, v184
	v_mov_b32_e32 v85, v185
	v_mov_b32_e32 v86, v186
	v_mov_b32_e32 v87, v187
	v_mov_b32_e32 v88, v188
	v_mov_b32_e32 v89, v189
	v_add_u32_e32 v66, 0x90, v140
	v_ashrrev_i32_e32 v67, 31, v66
	v_lshlrev_b64 v[102:103], 11, v[66:67]
	v_lshl_add_u64 v[66:67], v[142:143], 0, v[102:103]
	v_mov_b32_e32 v90, v216
	v_mov_b32_e32 v91, v217
	v_mov_b32_e32 v92, v218
	v_mov_b32_e32 v93, v219
	v_add_u32_e32 v68, 0xa0, v140
	v_add_u32_e32 v70, 0xb0, v140
	v_ashrrev_i32_e32 v69, 31, v68
	v_ashrrev_i32_e32 v71, 31, v70
	v_lshlrev_b64 v[80:81], 11, v[68:69]
	v_lshlrev_b64 v[78:79], 11, v[70:71]
	v_lshl_add_u64 v[68:69], v[142:143], 0, v[80:81]
	v_lshl_add_u64 v[104:105], v[142:143], 0, v[78:79]
	v_lshl_add_u64 v[106:107], s[78:79], 0, v[64:65]
	v_mov_b32_e32 v94, v220
	v_mov_b32_e32 v95, v221
	v_mov_b32_e32 v96, v222
	v_mov_b32_e32 v97, v223
	v_mov_b32_e32 v98, v236
	v_mov_b32_e32 v99, v237
	v_mov_b32_e32 v100, v238
	v_mov_b32_e32 v101, v239
	v_mov_b32_e32 v72, v240
	v_mov_b32_e32 v73, v241
	v_mov_b32_e32 v74, v242
	v_mov_b32_e32 v75, v243
	s_nop 0
	v_mov_b32_e32 v68, v246
	v_mov_b32_e32 v69, v247
	v_mov_b32_e32 v70, v248
	v_mov_b32_e32 v71, v249
	v_mov_b32_e32 v64, v250
	v_mov_b32_e32 v65, v251
	v_mov_b32_e32 v66, v252
	v_mov_b32_e32 v67, v253
	v_lshl_add_u64 v[104:105], v[106:107], 0, s[20:21]
	v_lshl_add_u64 v[104:105], v[104:105], 0, s[14:15]
	v_lshl_add_u64 v[104:105], v[104:105], 0, v[200:201]
	v_lshlrev_b32_e32 v106, 16, v82
	v_and_b32_e32 v107, 0xffff0000, v82
	v_lshlrev_b32_e32 v82, 16, v83
	v_and_b32_e32 v83, 0xffff0000, v83
	v_lshlrev_b32_e32 v108, 16, v84
	v_and_b32_e32 v109, 0xffff0000, v84
	v_lshlrev_b32_e32 v84, 16, v85
	v_and_b32_e32 v85, 0xffff0000, v85
	v_lshlrev_b32_e32 v110, 16, v86
	v_and_b32_e32 v111, 0xffff0000, v86
	v_lshlrev_b32_e32 v86, 16, v87
	v_and_b32_e32 v87, 0xffff0000, v87
	v_lshlrev_b32_e32 v112, 16, v88
	v_and_b32_e32 v113, 0xffff0000, v88
	v_lshlrev_b32_e32 v88, 16, v89
	v_and_b32_e32 v89, 0xffff0000, v89
	v_pk_fma_f32 v[62:63], v[62:63], 0.5, v[82:83] op_sel_hi:[1,0,1]
	v_pk_fma_f32 v[60:61], v[60:61], 0.5, v[106:107] op_sel_hi:[1,0,1]
	v_pk_fma_f32 v[58:59], v[58:59], 0.5, v[84:85] op_sel_hi:[1,0,1]
	v_pk_fma_f32 v[56:57], v[56:57], 0.5, v[108:109] op_sel_hi:[1,0,1]
	v_lshlrev_b32_e32 v114, 16, v90
	v_and_b32_e32 v115, 0xffff0000, v90
	v_lshlrev_b32_e32 v90, 16, v91
	v_and_b32_e32 v91, 0xffff0000, v91
	v_pk_fma_f32 v[82:83], v[50:51], 0.5, v[86:87] op_sel_hi:[1,0,1]
	v_pk_fma_f32 v[84:85], v[48:49], 0.5, v[110:111] op_sel_hi:[1,0,1]
	v_pk_fma_f32 v[86:87], v[46:47], 0.5, v[88:89] op_sel_hi:[1,0,1]
	v_pk_fma_f32 v[88:89], v[44:45], 0.5, v[112:113] op_sel_hi:[1,0,1]
	v_cvt_pk_bf16_f32 v44, v60, v61
	v_cvt_pk_bf16_f32 v45, v62, v63
	v_cvt_pk_bf16_f32 v46, v56, v57
	v_cvt_pk_bf16_f32 v47, v58, v59
	v_pk_fma_f32 v[54:55], v[54:55], 0.5, v[90:91] op_sel_hi:[1,0,1]
	v_cvt_pk_bf16_f32 v48, v84, v85
	v_cvt_pk_bf16_f32 v49, v82, v83
	v_cvt_pk_bf16_f32 v50, v88, v89
	v_cvt_pk_bf16_f32 v51, v86, v87
	global_store_dwordx4 v[104:105], v[44:47], off
	global_store_dwordx4 v[104:105], v[48:51], off offset:256
	v_pk_fma_f32 v[90:91], v[52:53], 0.5, v[114:115] op_sel_hi:[1,0,1]
	v_lshlrev_b32_e32 v46, 16, v92
	v_and_b32_e32 v47, 0xffff0000, v92
	v_cvt_pk_bf16_f32 v53, v54, v55
	v_mul_f32_e32 v55, v55, v55
	v_lshlrev_b32_e32 v48, 16, v93
	v_and_b32_e32 v49, 0xffff0000, v93
	v_pk_fma_f32 v[40:41], v[40:41], 0.5, v[46:47] op_sel_hi:[1,0,1]
	v_cvt_pk_bf16_f32 v52, v90, v91
	v_mul_f32_e32 v91, v91, v91
	v_fmac_f32_e32 v55, v54, v54
	v_pk_fma_f32 v[42:43], v[42:43], 0.5, v[48:49] op_sel_hi:[1,0,1]
	v_cvt_pk_bf16_f32 v54, v40, v41
	v_mul_f32_e32 v41, v41, v41
	v_fmac_f32_e32 v91, v90, v90
	v_fmac_f32_e32 v41, v40, v40
	v_mul_f32_e32 v40, v43, v43
	v_add_f32_e32 v50, v91, v55
	v_cvt_pk_bf16_f32 v55, v42, v43
	v_fmac_f32_e32 v40, v42, v42
	v_lshlrev_b32_e32 v42, 16, v94
	v_and_b32_e32 v43, 0xffff0000, v94
	v_lshlrev_b32_e32 v46, 16, v95
	v_and_b32_e32 v47, 0xffff0000, v95
	v_pk_fma_f32 v[42:43], v[36:37], 0.5, v[42:43] op_sel_hi:[1,0,1]
	v_pk_fma_f32 v[38:39], v[38:39], 0.5, v[46:47] op_sel_hi:[1,0,1]
	v_mul_f32_e32 v37, v43, v43
	v_cvt_pk_bf16_f32 v36, v42, v43
	v_fmac_f32_e32 v37, v42, v42
	v_mul_f32_e32 v42, v39, v39
	v_fmac_f32_e32 v42, v38, v38
	v_add_f32_e32 v37, v37, v42
	v_lshlrev_b32_e32 v42, 16, v96
	v_and_b32_e32 v43, 0xffff0000, v96
	v_lshlrev_b32_e32 v46, 16, v97
	v_and_b32_e32 v47, 0xffff0000, v97
	v_add_f32_e32 v40, v41, v40
	v_pk_fma_f32 v[34:35], v[34:35], 0.5, v[46:47] op_sel_hi:[1,0,1]
	v_pk_fma_f32 v[32:33], v[32:33], 0.5, v[42:43] op_sel_hi:[1,0,1]
	v_add_f32_e32 v48, v50, v40
	v_lshl_add_u64 v[40:41], s[78:79], 0, v[102:103]
	v_mul_f32_e32 v42, v33, v33
	v_mul_f32_e32 v43, v35, v35
	v_lshl_add_u64 v[40:41], v[40:41], 0, s[20:21]
	v_fmac_f32_e32 v42, v32, v32
	v_fmac_f32_e32 v43, v34, v34
	v_lshl_add_u64 v[40:41], v[40:41], 0, s[14:15]
	v_add_f32_e32 v37, v48, v37
	v_add_f32_e32 v42, v42, v43
	v_lshl_add_u64 v[40:41], v[40:41], 0, v[200:201]
	v_add_f32_e32 v42, v42, v37
	v_cvt_pk_bf16_f32 v37, v38, v39
	v_cvt_pk_bf16_f32 v38, v32, v33
	v_cvt_pk_bf16_f32 v39, v34, v35
	global_store_dwordx4 v[40:41], v[36:39], off offset:256
	v_lshlrev_b32_e32 v34, 16, v98
	v_and_b32_e32 v35, 0xffff0000, v98
	v_lshlrev_b32_e32 v36, 16, v99
	v_and_b32_e32 v37, 0xffff0000, v99
	v_pk_fma_f32 v[30:31], v[30:31], 0.5, v[36:37] op_sel_hi:[1,0,1]
	v_pk_fma_f32 v[34:35], v[28:29], 0.5, v[34:35] op_sel_hi:[1,0,1]
	v_cvt_pk_bf16_f32 v29, v30, v31
	v_cvt_pk_bf16_f32 v28, v34, v35
	v_mul_f32_e32 v35, v35, v35
	v_mul_f32_e32 v31, v31, v31
	v_fmac_f32_e32 v35, v34, v34
	v_fmac_f32_e32 v31, v30, v30
	v_add_f32_e32 v36, v35, v31
	v_lshlrev_b32_e32 v30, 16, v100
	v_and_b32_e32 v31, 0xffff0000, v100
	v_lshlrev_b32_e32 v34, 16, v101
	v_and_b32_e32 v35, 0xffff0000, v101
	v_pk_fma_f32 v[24:25], v[24:25], 0.5, v[30:31] op_sel_hi:[1,0,1]
	v_pk_fma_f32 v[26:27], v[26:27], 0.5, v[34:35] op_sel_hi:[1,0,1]
	v_cvt_pk_bf16_f32 v30, v24, v25
	v_mul_f32_e32 v25, v25, v25
	v_fmac_f32_e32 v25, v24, v24
	v_mul_f32_e32 v24, v27, v27
	v_fmac_f32_e32 v24, v26, v26
	v_add_f32_e32 v24, v25, v24
	v_add_f32_e32 v34, v36, v24
	v_lshl_add_u64 v[24:25], s[78:79], 0, v[80:81]
	v_lshl_add_u64 v[24:25], v[24:25], 0, s[20:21]
	v_lshl_add_u64 v[24:25], v[24:25], 0, s[14:15]
	v_cvt_pk_bf16_f32 v31, v26, v27
	v_lshl_add_u64 v[24:25], v[24:25], 0, v[200:201]
	v_lshlrev_b32_e32 v26, 16, v72
	v_and_b32_e32 v27, 0xffff0000, v72
	global_store_dwordx4 v[24:25], v[28:31], off
	v_pk_fma_f32 v[26:27], v[20:21], 0.5, v[26:27] op_sel_hi:[1,0,1]
	v_mul_f32_e32 v61, v61, v61
	v_lshlrev_b32_e32 v28, 16, v73
	v_and_b32_e32 v29, 0xffff0000, v73
	v_pk_fma_f32 v[22:23], v[22:23], 0.5, v[28:29] op_sel_hi:[1,0,1]
	v_mul_f32_e32 v21, v27, v27
	v_cvt_pk_bf16_f32 v20, v26, v27
	v_fmac_f32_e32 v21, v26, v26
	v_mul_f32_e32 v26, v23, v23
	v_fmac_f32_e32 v26, v22, v22
	v_add_f32_e32 v21, v21, v26
	v_lshlrev_b32_e32 v26, 16, v74
	v_and_b32_e32 v27, 0xffff0000, v74
	v_lshlrev_b32_e32 v28, 16, v75
	v_and_b32_e32 v29, 0xffff0000, v75
	v_pk_fma_f32 v[18:19], v[18:19], 0.5, v[28:29] op_sel_hi:[1,0,1]
	v_pk_fma_f32 v[16:17], v[16:17], 0.5, v[26:27] op_sel_hi:[1,0,1]
	v_mul_f32_e32 v27, v19, v19
	v_mul_f32_e32 v26, v17, v17
	v_fmac_f32_e32 v26, v16, v16
	v_fmac_f32_e32 v27, v18, v18
	v_add_f32_e32 v21, v34, v21
	v_add_f32_e32 v26, v26, v27
	v_add_f32_e32 v26, v26, v21
	v_cvt_pk_bf16_f32 v21, v22, v23
	v_cvt_pk_bf16_f32 v22, v16, v17
	v_cvt_pk_bf16_f32 v23, v18, v19
	global_store_dwordx4 v[24:25], v[20:23], off offset:256
	v_lshlrev_b32_e32 v18, 16, v68
	v_and_b32_e32 v19, 0xffff0000, v68
	v_lshlrev_b32_e32 v20, 16, v69
	v_and_b32_e32 v21, 0xffff0000, v69
	v_pk_fma_f32 v[14:15], v[14:15], 0.5, v[20:21] op_sel_hi:[1,0,1]
	v_pk_fma_f32 v[18:19], v[12:13], 0.5, v[18:19] op_sel_hi:[1,0,1]
	v_cvt_pk_bf16_f32 v13, v14, v15
	v_cvt_pk_bf16_f32 v12, v18, v19
	v_mul_f32_e32 v19, v19, v19
	v_mul_f32_e32 v15, v15, v15
	v_fmac_f32_e32 v19, v18, v18
	v_fmac_f32_e32 v15, v14, v14
	v_add_f32_e32 v20, v19, v15
	v_lshlrev_b32_e32 v14, 16, v70
	v_and_b32_e32 v15, 0xffff0000, v70
	v_lshlrev_b32_e32 v18, 16, v71
	v_and_b32_e32 v19, 0xffff0000, v71
	v_pk_fma_f32 v[8:9], v[8:9], 0.5, v[14:15] op_sel_hi:[1,0,1]
	v_pk_fma_f32 v[10:11], v[10:11], 0.5, v[18:19] op_sel_hi:[1,0,1]
	v_cvt_pk_bf16_f32 v14, v8, v9
	v_mul_f32_e32 v9, v9, v9
	v_fmac_f32_e32 v9, v8, v8
	v_mul_f32_e32 v8, v11, v11
	v_cvt_pk_bf16_f32 v15, v10, v11
	v_fmac_f32_e32 v8, v10, v10
	v_lshlrev_b32_e32 v10, 16, v64
	v_and_b32_e32 v11, 0xffff0000, v64
	v_lshlrev_b32_e32 v18, 16, v65
	v_and_b32_e32 v19, 0xffff0000, v65
	v_pk_fma_f32 v[6:7], v[6:7], 0.5, v[18:19] op_sel_hi:[1,0,1]
	v_pk_fma_f32 v[4:5], v[4:5], 0.5, v[10:11] op_sel_hi:[1,0,1]
	v_mul_f32_e32 v11, v7, v7
	v_mul_f32_e32 v10, v5, v5
	v_add_f32_e32 v8, v9, v8
	v_fmac_f32_e32 v10, v4, v4
	v_fmac_f32_e32 v11, v6, v6
	v_add_f32_e32 v20, v20, v8
	v_add_f32_e32 v10, v10, v11
	v_mul_f32_e32 v63, v63, v63
	v_mul_f32_e32 v57, v57, v57
	v_mul_f32_e32 v59, v59, v59
	v_add_f32_e32 v20, v20, v10
	v_lshlrev_b32_e32 v10, 16, v66
	v_and_b32_e32 v11, 0xffff0000, v66
	v_lshlrev_b32_e32 v18, 16, v67
	v_and_b32_e32 v19, 0xffff0000, v67
	v_mul_f32_e32 v85, v85, v85
	v_mul_f32_e32 v83, v83, v83
	v_fmac_f32_e32 v61, v60, v60
	v_fmac_f32_e32 v63, v62, v62
	v_fmac_f32_e32 v57, v56, v56
	v_fmac_f32_e32 v59, v58, v58
	v_pk_fma_f32 v[18:19], v[2:3], 0.5, v[18:19] op_sel_hi:[1,0,1]
	v_pk_fma_f32 v[10:11], v[0:1], 0.5, v[10:11] op_sel_hi:[1,0,1]
	v_mul_f32_e32 v89, v89, v89
	v_mul_f32_e32 v87, v87, v87
	v_fmac_f32_e32 v85, v84, v84
	v_fmac_f32_e32 v83, v82, v82
	v_add_f32_e32 v56, v61, v63
	v_add_f32_e32 v57, v57, v59
	v_mul_f32_e32 v0, v11, v11
	v_mul_f32_e32 v1, v19, v19
	v_fmac_f32_e32 v89, v88, v88
	v_fmac_f32_e32 v87, v86, v86
	v_add_f32_e32 v58, v85, v83
	v_add_f32_e32 v56, v56, v57
	v_fmac_f32_e32 v0, v10, v10
	v_fmac_f32_e32 v1, v18, v18
	v_add_f32_e32 v59, v89, v87
	v_add_f32_e32 v56, v56, v58
	v_add_f32_e32 v0, v0, v1
	v_add_f32_e32 v56, v59, v56
	v_add_f32_e32 v3, v0, v20
	ds_bpermute_b32 v57, v148, v56
	ds_bpermute_b32 v43, v148, v42
	ds_bpermute_b32 v27, v148, v26
	ds_bpermute_b32 v20, v148, v3
	v_lshl_add_u64 v[8:9], s[78:79], 0, v[78:79]
	v_lshl_add_u64 v[8:9], v[8:9], 0, s[20:21]
	v_lshl_add_u64 v[0:1], v[8:9], 0, s[14:15]
	s_waitcnt lgkmcnt(3)
	v_add_f32_e32 v44, v56, v57
	s_waitcnt lgkmcnt(2)
	v_add_f32_e32 v32, v42, v43
	s_waitcnt lgkmcnt(1)
	v_add_f32_e32 v16, v26, v27
	v_lshl_add_u64 v[8:9], v[0:1], 0, v[200:201]
	s_waitcnt lgkmcnt(0)
	v_add_f32_e32 v0, v3, v20
	ds_bpermute_b32 v45, v141, v44
	ds_bpermute_b32 v33, v141, v32
	ds_bpermute_b32 v17, v141, v16
	ds_bpermute_b32 v1, v141, v0
	v_cvt_pk_bf16_f32 v2, v4, v5
	v_cvt_pk_bf16_f32 v3, v6, v7
	v_cvt_pk_bf16_f32 v4, v10, v11
	v_cvt_pk_bf16_f32 v5, v18, v19
	global_store_dwordx4 v[40:41], v[52:55], off
	global_store_dwordx4 v[8:9], v[12:15], off
	global_store_dwordx4 v[8:9], v[2:5], off offset:256
	s_and_saveexec_b64 s[20:21], s[2:3]
	s_cbranch_execz .LBB0_1723
	s_waitcnt lgkmcnt(3)
	v_add_f32_e32 v3, v44, v45
	s_waitcnt lgkmcnt(0)
	v_add_f32_e32 v0, v0, v1
	v_add_f32_e32 v1, v16, v17
	v_add_f32_e32 v2, v32, v33
	global_atomic_add_f32 v[76:77], v3, off offset:512
	global_atomic_add_f32 v[76:77], v2, off offset:576
	global_atomic_add_f32 v[76:77], v1, off offset:640
	global_atomic_add_f32 v[76:77], v0, off offset:704

	.amdhsa_kernel _Z4mega1Pii
		.amdhsa_group_segment_fixed_size 0
		.amdhsa_private_segment_fixed_size 0
		.amdhsa_kernarg_size 616
		.amdhsa_user_sgpr_count 2
		.amdhsa_user_sgpr_dispatch_ptr 0
		.amdhsa_user_sgpr_queue_ptr 0
		.amdhsa_user_sgpr_kernarg_segment_ptr 1
		.amdhsa_user_sgpr_dispatch_id 0
		.amdhsa_user_sgpr_kernarg_preload_length 0
		.amdhsa_user_sgpr_kernarg_preload_offset 0
		.amdhsa_user_sgpr_private_segment_size 0
		.amdhsa_uses_dynamic_stack 0
		.amdhsa_enable_private_segment 0
		.amdhsa_system_sgpr_workgroup_id_x 1
		.amdhsa_system_sgpr_workgroup_id_y 0
		.amdhsa_system_sgpr_workgroup_id_z 0
		.amdhsa_system_sgpr_workgroup_info 0
		.amdhsa_system_vgpr_workitem_id 2
		.amdhsa_next_free_vgpr 256
		.amdhsa_next_free_sgpr 100
		.amdhsa_accum_offset 256
		.amdhsa_reserve_vcc 1
		.amdhsa_float_round_mode_32 0
		.amdhsa_float_round_mode_16_64 0
		.amdhsa_float_denorm_mode_32 3
		.amdhsa_float_denorm_mode_16_64 3
		.amdhsa_dx10_clamp 1
		.amdhsa_ieee_mode 1
		.amdhsa_fp16_overflow 0
		.amdhsa_tg_split 0
		.amdhsa_exception_fp_ieee_invalid_op 0
		.amdhsa_exception_fp_denorm_src 0
		.amdhsa_exception_fp_ieee_div_zero 0
		.amdhsa_exception_fp_ieee_overflow 0
		.amdhsa_exception_fp_ieee_underflow 0
		.amdhsa_exception_fp_ieee_inexact 0
		.amdhsa_exception_int_div_zero 0
	.end_amdhsa_kernel

amdhsa.kernels:
  - .agpr_count:     0
    .args:
      - .offset:         0
        .size:           352
        .value_kind:     by_value
      - .offset:         352
        .size:           4
        .value_kind:     by_value
      - .offset:         356
        .size:           4
        .value_kind:     by_value
      - .offset:         360
        .size:           4
        .value_kind:     hidden_block_count_x
      - .offset:         364
        .size:           4
        .value_kind:     hidden_block_count_y
      - .offset:         368
        .size:           4
        .value_kind:     hidden_block_count_z
      - .offset:         372
        .size:           2
        .value_kind:     hidden_group_size_x
      - .offset:         374
        .size:           2
        .value_kind:     hidden_group_size_y
      - .offset:         376
        .size:           2
        .value_kind:     hidden_group_size_z
      - .offset:         378
        .size:           2
        .value_kind:     hidden_remainder_x
      - .offset:         380
        .size:           2
        .value_kind:     hidden_remainder_y
      - .offset:         382
        .size:           2
        .value_kind:     hidden_remainder_z
      - .offset:         400
        .size:           8
        .value_kind:     hidden_global_offset_x
      - .offset:         408
        .size:           8
        .value_kind:     hidden_global_offset_y
      - .offset:         416
        .size:           8
        .value_kind:     hidden_global_offset_z
      - .offset:         424
        .size:           2
        .value_kind:     hidden_grid_dims
      - .offset:         448
        .size:           8
        .value_kind:     hidden_multigrid_sync_arg
      - .offset:         480
        .size:           4
        .value_kind:     hidden_dynamic_lds_size
    .group_segment_fixed_size: 0
    .kernarg_segment_align: 8
    .kernarg_segment_size: 616
    .language:       OpenCL C
    .language_version:
      - 2
      - 0
    .max_flat_workgroup_size: 512
    .name:           _Z4mega1Pii
    .private_segment_fixed_size: 0
    .sgpr_count:     104
    .sgpr_spill_count: 85
    .symbol:         _Z4mega1Pii.kd
    .uniform_work_group_size: 1
    .uses_dynamic_stack: false
    .vgpr_count:     256
    .vgpr_spill_count: 0
    .wavefront_size: 64
